# snake MFMA order + nt hint on f32 residual-stream stores of P2/P8 epilogues
# speedup vs baseline: 1.0014x; 1.0014x over previous
.LBB0_232:
	v_lshl_add_u32 v64, s54, 8, v216
	v_lshl_or_b32 v140, s55, 8, v218
	v_ashrrev_i32_e32 v65, 31, v64
	v_readlane_b32 s60, v252, 0
	v_ashrrev_i32_e32 v141, 31, v140
	s_waitcnt lgkmcnt(0)
	v_lshlrev_b64 v[0:1], 13, v[64:65]
	v_readlane_b32 s61, v252, 1
	v_lshlrev_b64 v[16:17], 2, v[140:141]
	v_readlane_b32 s74, v252, 14
	v_lshl_add_u64 v[212:213], s[60:61], 0, v[0:1]
	v_lshl_add_u64 v[0:1], v[212:213], 0, v[16:17]
	v_readlane_b32 s75, v252, 15
	global_load_dwordx4 v[28:31], v[0:1], off
	global_load_dwordx4 v[40:43], v[0:1], off offset:64
	global_load_dwordx4 v[52:55], v[0:1], off offset:512
	v_lshl_add_u64 v[2:3], s[74:75], 0, v[16:17]
	global_load_dwordx4 v[12:15], v[2:3], off
	global_load_dwordx4 v[8:11], v[2:3], off offset:64
	global_load_dwordx4 v[4:7], v[2:3], off offset:512
	global_load_dwordx4 v[60:63], v[0:1], off offset:576
	v_or_b32_e32 v66, 16, v64
	v_or_b32_e32 v214, 32, v64
	v_ashrrev_i32_e32 v67, 31, v66
	v_ashrrev_i32_e32 v215, 31, v214
	v_lshlrev_b64 v[18:19], 13, v[66:67]
	v_lshlrev_b64 v[20:21], 13, v[214:215]
	v_lshl_add_u64 v[18:19], s[60:61], 0, v[18:19]
	v_lshl_add_u64 v[20:21], s[60:61], 0, v[20:21]
	global_load_dwordx4 v[0:3], v[2:3], off offset:576
	v_lshl_add_u64 v[18:19], v[18:19], 0, v[16:17]
	v_lshl_add_u64 v[16:17], v[20:21], 0, v[16:17]
	global_load_dwordx4 v[56:59], v[18:19], off
	global_load_dwordx4 v[48:51], v[18:19], off offset:64
	global_load_dwordx4 v[36:39], v[18:19], off offset:512
	global_load_dwordx4 v[24:27], v[18:19], off offset:576
	global_load_dwordx4 v[44:47], v[16:17], off
	global_load_dwordx4 v[32:35], v[16:17], off offset:64
	global_load_dwordx4 v[20:23], v[16:17], off offset:512
	s_nop 0
	global_load_dwordx4 v[16:19], v[16:17], off offset:576
	v_and_b32_e32 v225, 64, v223
	v_xor_b32_e32 v224, 16, v223
	v_add_u32_e32 v225, 64, v225
	v_xor_b32_e32 v226, 32, v223
	v_cmp_lt_i32_e32 vcc, v224, v225
	v_readlane_b32 s62, v252, 2
	v_readlane_b32 s63, v252, 3
	v_readlane_b32 s64, v252, 4
	v_readlane_b32 s65, v252, 5
	v_readlane_b32 s66, v252, 6
	v_readlane_b32 s67, v252, 7
	v_readlane_b32 s68, v252, 8
	v_readlane_b32 s69, v252, 9
	v_readlane_b32 s70, v252, 10
	v_readlane_b32 s71, v252, 11
	v_readlane_b32 s72, v252, 12
	v_readlane_b32 s73, v252, 13
	v_cndmask_b32_e32 v224, v223, v224, vcc
	v_cmp_lt_i32_e32 vcc, v226, v225
	v_readlane_b32 s60, v252, 16
	v_readlane_b32 s74, v252, 30
	v_cndmask_b32_e32 v228, v223, v226, vcc
	v_lshlrev_b64 v[226:227], 11, v[64:65]
	v_lshl_add_u64 v[226:227], v[226:227], 0, v[140:141]
	v_readlane_b32 s75, v252, 31
	v_lshlrev_b32_e32 v225, 2, v224
	v_lshlrev_b32_e32 v224, 2, v228
	v_lshl_add_u64 v[228:229], v[226:227], 2, s[74:75]
	v_lshlrev_b64 v[226:227], 1, v[226:227]
	v_lshl_add_u64 v[230:231], s[12:13], 0, v[226:227]
	v_or_b32_e32 v232, 32, v226
	v_mov_b32_e32 v233, v227
	v_lshl_add_u64 v[232:233], s[12:13], 0, v[232:233]
	v_readlane_b32 s61, v252, 17
	v_readlane_b32 s62, v252, 18
	v_readlane_b32 s63, v252, 19
	v_readlane_b32 s64, v252, 20
	v_readlane_b32 s65, v252, 21
	v_readlane_b32 s66, v252, 22
	v_readlane_b32 s67, v252, 23
	v_readlane_b32 s68, v252, 24
	v_readlane_b32 s69, v252, 25
	v_readlane_b32 s70, v252, 26
	v_readlane_b32 s71, v252, 27
	v_readlane_b32 s72, v252, 28
	v_readlane_b32 s73, v252, 29
	s_waitcnt vmcnt(0)
	v_pk_add_f32 v[30:31], v[200:201], v[30:31]
	v_pk_add_f32 v[28:29], v[202:203], v[28:29]
	v_pk_add_f32 v[42:43], v[204:205], v[42:43]
	v_pk_add_f32 v[40:41], v[206:207], v[40:41]
	v_pk_add_f32 v[54:55], v[210:211], v[54:55]
	v_pk_add_f32 v[52:53], v[208:209], v[52:53]
	v_mul_f32_e32 v234, v29, v29
	v_mul_f32_e32 v235, v31, v31
	v_pk_mul_f32 v[200:201], v[14:15], v[30:31]
	v_pk_mul_f32 v[202:203], v[12:13], v[28:29]
	v_mul_f32_e32 v236, v41, v41
	v_mul_f32_e32 v237, v43, v43
	global_store_dwordx4 v[228:229], v[28:31], off nt
	v_pk_mul_f32 v[204:205], v[10:11], v[42:43]
	v_pk_mul_f32 v[206:207], v[8:9], v[40:41]
	v_mul_f32_e32 v238, v53, v53
	v_mul_f32_e32 v239, v55, v55
	v_fmac_f32_e32 v234, v28, v28
	v_fmac_f32_e32 v235, v30, v30
	v_cvt_pk_bf16_f32 v28, v202, v203
	v_cvt_pk_bf16_f32 v29, v200, v201
	v_fmac_f32_e32 v236, v40, v40
	v_fmac_f32_e32 v237, v42, v42
	v_cvt_pk_bf16_f32 v30, v206, v207
	v_cvt_pk_bf16_f32 v31, v204, v205
	v_fmac_f32_e32 v238, v52, v52
	v_fmac_f32_e32 v239, v54, v54
	v_add_f32_e32 v200, v234, v235
	global_store_dwordx2 v[230:231], v[28:29], off
	global_store_dwordx4 v[228:229], v[40:43], off offset:64 nt
	v_add_f32_e32 v28, v236, v237
	v_pk_mul_f32 v[208:209], v[6:7], v[54:55]
	v_pk_mul_f32 v[210:211], v[4:5], v[52:53]
	global_store_dwordx2 v[232:233], v[30:31], off
	global_store_dwordx4 v[228:229], v[52:55], off offset:512 nt
	v_add_f32_e32 v29, v238, v239
	v_add_f32_e32 v28, v200, v28
	v_or_b32_e32 v30, 0x100, v226
	v_mov_b32_e32 v31, v227
	v_add_f32_e32 v40, v28, v29
	v_cvt_pk_bf16_f32 v28, v210, v211
	v_cvt_pk_bf16_f32 v29, v208, v209
	v_lshl_add_u64 v[30:31], s[12:13], 0, v[30:31]
	global_store_dwordx2 v[30:31], v[28:29], off
	v_pk_add_f32 v[30:31], v[198:199], v[62:63]
	v_pk_add_f32 v[28:29], v[196:197], v[60:61]
	v_mul_f32_e32 v42, v31, v31
	v_mul_f32_e32 v41, v29, v29
	v_fmac_f32_e32 v41, v28, v28
	v_fmac_f32_e32 v42, v30, v30
	v_add_f32_e32 v41, v41, v42
	v_add_f32_e32 v41, v40, v41
	ds_bpermute_b32 v42, v225, v41
	global_store_dwordx4 v[228:229], v[28:31], off offset:576 nt
	v_or_b32_e32 v226, 0x120, v226
	s_nop 0
	v_pk_mul_f32 v[28:29], v[0:1], v[28:29]
	v_pk_mul_f32 v[30:31], v[2:3], v[30:31]
	v_cvt_pk_bf16_f32 v40, v28, v29
	s_waitcnt lgkmcnt(0)
	v_add_f32_e32 v28, v41, v42
	ds_bpermute_b32 v29, v224, v28
	v_cvt_pk_bf16_f32 v41, v30, v31
	v_lshl_add_u64 v[30:31], s[12:13], 0, v[226:227]
	global_store_dwordx2 v[30:31], v[40:41], off
	s_and_saveexec_b64 s[24:25], s[4:5]
	s_cbranch_execz .LBB0_234
	v_lshl_add_u64 v[30:31], v[64:65], 2, s[14:15]
	s_waitcnt lgkmcnt(0)
	v_add_f32_e32 v28, v28, v29
	global_atomic_add_f32 v[30:31], v28, off
.LBB0_234:
	s_or_b64 exec, exec, s[24:25]
	v_or_b32_e32 v196, 48, v64
	v_ashrrev_i32_e32 v197, 31, v196
	v_readlane_b32 s60, v252, 0
	s_waitcnt lgkmcnt(0)
	v_lshlrev_b64 v[28:29], 13, v[196:197]
	v_readlane_b32 s61, v252, 1
	v_readlane_b32 s62, v252, 2
	v_readlane_b32 s63, v252, 3
	v_lshl_add_u64 v[28:29], s[60:61], 0, v[28:29]
	v_lshl_add_u64 v[28:29], v[140:141], 2, v[28:29]
	global_load_dwordx4 v[60:63], v[28:29], off
	global_load_dwordx4 v[52:55], v[28:29], off offset:64
	global_load_dwordx4 v[40:43], v[28:29], off offset:512
	s_nop 0
	global_load_dwordx4 v[28:31], v[28:29], off offset:576
	v_readlane_b32 s64, v252, 4
	v_readlane_b32 s65, v252, 5
	v_readlane_b32 s66, v252, 6
	v_readlane_b32 s67, v252, 7
	v_readlane_b32 s68, v252, 8
	v_readlane_b32 s69, v252, 9
	v_readlane_b32 s70, v252, 10
	v_readlane_b32 s71, v252, 11
	v_readlane_b32 s72, v252, 12
	v_readlane_b32 s73, v252, 13
	v_readlane_b32 s74, v252, 14
	v_readlane_b32 s75, v252, 15
	v_lshlrev_b64 v[198:199], 11, v[66:67]
	v_readlane_b32 s60, v252, 16
	v_lshl_add_u64 v[198:199], v[198:199], 0, v[140:141]
	v_pk_add_f32 v[58:59], v[194:195], v[58:59]
	v_pk_add_f32 v[56:57], v[192:193], v[56:57]
	v_readlane_b32 s74, v252, 30
	v_readlane_b32 s75, v252, 31
	v_mul_f32_e32 v65, v57, v57
	v_mul_f32_e32 v194, v59, v59
	v_lshl_add_u64 v[192:193], v[198:199], 2, s[74:75]
	global_store_dwordx4 v[192:193], v[56:59], off nt
	v_fmac_f32_e32 v65, v56, v56
	v_fmac_f32_e32 v194, v58, v58
	v_pk_mul_f32 v[58:59], v[14:15], v[58:59]
	v_pk_mul_f32 v[56:57], v[12:13], v[56:57]
	v_add_f32_e32 v65, v65, v194
	v_cvt_pk_bf16_f32 v56, v56, v57
	v_cvt_pk_bf16_f32 v57, v58, v59
	v_lshlrev_b64 v[58:59], 1, v[198:199]
	v_lshl_add_u64 v[194:195], s[12:13], 0, v[58:59]
	v_pk_add_f32 v[50:51], v[190:191], v[50:51]
	v_pk_add_f32 v[48:49], v[188:189], v[48:49]
	global_store_dwordx2 v[194:195], v[56:57], off
	v_mul_f32_e32 v56, v49, v49
	v_mul_f32_e32 v57, v51, v51
	global_store_dwordx4 v[192:193], v[48:51], off offset:64 nt
	v_fmac_f32_e32 v56, v48, v48
	v_fmac_f32_e32 v57, v50, v50
	v_pk_mul_f32 v[50:51], v[10:11], v[50:51]
	v_pk_mul_f32 v[48:49], v[8:9], v[48:49]
	v_pk_add_f32 v[38:39], v[186:187], v[38:39]
	v_cvt_pk_bf16_f32 v48, v48, v49
	v_cvt_pk_bf16_f32 v49, v50, v51
	v_or_b32_e32 v50, 32, v58
	v_mov_b32_e32 v51, v59
	v_lshl_add_u64 v[50:51], s[12:13], 0, v[50:51]
	v_pk_add_f32 v[36:37], v[184:185], v[36:37]
	global_store_dwordx2 v[50:51], v[48:49], off
	v_mul_f32_e32 v48, v37, v37
	v_mul_f32_e32 v49, v39, v39
	global_store_dwordx4 v[192:193], v[36:39], off offset:512 nt
	v_fmac_f32_e32 v48, v36, v36
	v_fmac_f32_e32 v49, v38, v38
	v_pk_mul_f32 v[38:39], v[6:7], v[38:39]
	v_pk_mul_f32 v[36:37], v[4:5], v[36:37]
	v_pk_add_f32 v[26:27], v[182:183], v[26:27]
	v_cvt_pk_bf16_f32 v36, v36, v37
	v_cvt_pk_bf16_f32 v37, v38, v39
	v_or_b32_e32 v38, 0x100, v58
	v_mov_b32_e32 v39, v59
	v_lshl_add_u64 v[38:39], s[12:13], 0, v[38:39]
	v_pk_add_f32 v[24:25], v[180:181], v[24:25]
	v_add_f32_e32 v56, v56, v57
	global_store_dwordx2 v[38:39], v[36:37], off
	v_mul_f32_e32 v36, v25, v25
	v_mul_f32_e32 v37, v27, v27
	v_add_f32_e32 v56, v65, v56
	v_add_f32_e32 v48, v48, v49
	v_fmac_f32_e32 v36, v24, v24
	v_fmac_f32_e32 v37, v26, v26
	v_add_f32_e32 v48, v56, v48
	v_add_f32_e32 v36, v36, v37
	v_add_f32_e32 v37, v48, v36
	ds_bpermute_b32 v38, v225, v37
	global_store_dwordx4 v[192:193], v[24:27], off offset:576 nt
	v_or_b32_e32 v58, 0x120, v58
	v_readlane_b32 s61, v252, 17
	v_pk_mul_f32 v[24:25], v[0:1], v[24:25]
	v_pk_mul_f32 v[26:27], v[2:3], v[26:27]
	v_cvt_pk_bf16_f32 v36, v24, v25
	s_waitcnt lgkmcnt(0)
	v_add_f32_e32 v24, v37, v38
	ds_bpermute_b32 v25, v224, v24
	v_cvt_pk_bf16_f32 v37, v26, v27
	v_lshl_add_u64 v[26:27], s[12:13], 0, v[58:59]
	v_readlane_b32 s62, v252, 18
	v_readlane_b32 s63, v252, 19
	v_readlane_b32 s64, v252, 20
	v_readlane_b32 s65, v252, 21
	v_readlane_b32 s66, v252, 22
	v_readlane_b32 s67, v252, 23
	v_readlane_b32 s68, v252, 24
	v_readlane_b32 s69, v252, 25
	v_readlane_b32 s70, v252, 26
	v_readlane_b32 s71, v252, 27
	v_readlane_b32 s72, v252, 28
	v_readlane_b32 s73, v252, 29
	global_store_dwordx2 v[26:27], v[36:37], off
	s_and_saveexec_b64 s[24:25], s[4:5]
	s_cbranch_execz .LBB0_236
	v_lshl_add_u64 v[26:27], v[66:67], 2, s[14:15]
	s_waitcnt lgkmcnt(0)
	v_add_f32_e32 v24, v24, v25
	global_atomic_add_f32 v[26:27], v24, off
.LBB0_236:
	s_or_b64 exec, exec, s[24:25]
	v_add_u32_e32 v180, 0x80, v64
	v_ashrrev_i32_e32 v181, 31, v180
	v_readlane_b32 s60, v252, 0
	s_waitcnt lgkmcnt(0)
	v_lshlrev_b64 v[24:25], 13, v[180:181]
	v_readlane_b32 s61, v252, 1
	v_readlane_b32 s62, v252, 2
	v_readlane_b32 s63, v252, 3
	v_lshl_add_u64 v[24:25], s[60:61], 0, v[24:25]
	v_lshl_add_u64 v[24:25], v[140:141], 2, v[24:25]
	global_load_dwordx4 v[64:67], v[24:25], off
	global_load_dwordx4 v[48:51], v[24:25], off offset:64
	global_load_dwordx4 v[36:39], v[24:25], off offset:512
	s_nop 0
	global_load_dwordx4 v[24:27], v[24:25], off offset:576
	v_readlane_b32 s64, v252, 4
	v_readlane_b32 s65, v252, 5
	v_readlane_b32 s66, v252, 6
	v_readlane_b32 s67, v252, 7
	v_readlane_b32 s68, v252, 8
	v_readlane_b32 s69, v252, 9
	v_readlane_b32 s70, v252, 10
	v_readlane_b32 s71, v252, 11
	v_readlane_b32 s72, v252, 12
	v_readlane_b32 s73, v252, 13
	v_readlane_b32 s74, v252, 14
	v_readlane_b32 s75, v252, 15
	v_lshlrev_b64 v[56:57], 11, v[214:215]
	v_readlane_b32 s60, v252, 16
	v_lshl_add_u64 v[56:57], v[56:57], 0, v[140:141]
	v_pk_add_f32 v[46:47], v[178:179], v[46:47]
	v_pk_add_f32 v[44:45], v[176:177], v[44:45]
	v_readlane_b32 s74, v252, 30
	v_readlane_b32 s75, v252, 31
	v_mul_f32_e32 v176, v45, v45
	v_mul_f32_e32 v177, v47, v47
	v_lshl_add_u64 v[58:59], v[56:57], 2, s[74:75]
	global_store_dwordx4 v[58:59], v[44:47], off nt
	v_fmac_f32_e32 v176, v44, v44
	v_fmac_f32_e32 v177, v46, v46
	v_pk_mul_f32 v[46:47], v[14:15], v[46:47]
	v_pk_mul_f32 v[44:45], v[12:13], v[44:45]
	v_pk_add_f32 v[34:35], v[174:175], v[34:35]
	v_cvt_pk_bf16_f32 v44, v44, v45
	v_cvt_pk_bf16_f32 v45, v46, v47
	v_lshlrev_b64 v[46:47], 1, v[56:57]
	v_lshl_add_u64 v[56:57], s[12:13], 0, v[46:47]
	v_pk_add_f32 v[32:33], v[172:173], v[32:33]
	global_store_dwordx2 v[56:57], v[44:45], off
	v_mul_f32_e32 v44, v33, v33
	v_mul_f32_e32 v45, v35, v35
	global_store_dwordx4 v[58:59], v[32:35], off offset:64 nt
	v_fmac_f32_e32 v44, v32, v32
	v_fmac_f32_e32 v45, v34, v34
	v_pk_mul_f32 v[34:35], v[10:11], v[34:35]
	v_pk_mul_f32 v[32:33], v[8:9], v[32:33]
	v_pk_add_f32 v[22:23], v[170:171], v[22:23]
	v_cvt_pk_bf16_f32 v32, v32, v33
	v_cvt_pk_bf16_f32 v33, v34, v35
	v_or_b32_e32 v34, 32, v46
	v_mov_b32_e32 v35, v47
	v_lshl_add_u64 v[34:35], s[12:13], 0, v[34:35]
	v_pk_add_f32 v[20:21], v[168:169], v[20:21]
	global_store_dwordx2 v[34:35], v[32:33], off
	v_mul_f32_e32 v32, v21, v21
	v_mul_f32_e32 v33, v23, v23
	global_store_dwordx4 v[58:59], v[20:23], off offset:512 nt
	v_fmac_f32_e32 v32, v20, v20
	v_fmac_f32_e32 v33, v22, v22
	v_pk_mul_f32 v[22:23], v[6:7], v[22:23]
	v_pk_mul_f32 v[20:21], v[4:5], v[20:21]
	v_pk_add_f32 v[18:19], v[166:167], v[18:19]
	v_cvt_pk_bf16_f32 v20, v20, v21
	v_cvt_pk_bf16_f32 v21, v22, v23
	v_or_b32_e32 v22, 0x100, v46
	v_mov_b32_e32 v23, v47
	v_lshl_add_u64 v[22:23], s[12:13], 0, v[22:23]
	v_pk_add_f32 v[16:17], v[164:165], v[16:17]
	v_add_f32_e32 v176, v176, v177
	v_add_f32_e32 v44, v44, v45
	global_store_dwordx2 v[22:23], v[20:21], off
	v_mul_f32_e32 v20, v17, v17
	v_mul_f32_e32 v21, v19, v19
	v_add_f32_e32 v44, v176, v44
	v_add_f32_e32 v32, v32, v33
	v_fmac_f32_e32 v20, v16, v16
	v_fmac_f32_e32 v21, v18, v18
	v_add_f32_e32 v32, v44, v32
	v_add_f32_e32 v20, v20, v21
	v_add_f32_e32 v21, v32, v20
	ds_bpermute_b32 v22, v225, v21
	global_store_dwordx4 v[58:59], v[16:19], off offset:576 nt
	v_or_b32_e32 v46, 0x120, v46
	v_readlane_b32 s61, v252, 17
	v_pk_mul_f32 v[16:17], v[0:1], v[16:17]
	v_pk_mul_f32 v[18:19], v[2:3], v[18:19]
	v_cvt_pk_bf16_f32 v20, v16, v17
	s_waitcnt lgkmcnt(0)
	v_add_f32_e32 v16, v21, v22
	ds_bpermute_b32 v17, v224, v16
	v_cvt_pk_bf16_f32 v21, v18, v19
	v_lshl_add_u64 v[18:19], s[12:13], 0, v[46:47]
	v_readlane_b32 s62, v252, 18
	v_readlane_b32 s63, v252, 19
	v_readlane_b32 s64, v252, 20
	v_readlane_b32 s65, v252, 21
	v_readlane_b32 s66, v252, 22
	v_readlane_b32 s67, v252, 23
	v_readlane_b32 s68, v252, 24
	v_readlane_b32 s69, v252, 25
	v_readlane_b32 s70, v252, 26
	v_readlane_b32 s71, v252, 27
	v_readlane_b32 s72, v252, 28
	v_readlane_b32 s73, v252, 29
	global_store_dwordx2 v[18:19], v[20:21], off
	s_and_saveexec_b64 s[24:25], s[4:5]
	s_cbranch_execz .LBB0_238
	v_lshl_add_u64 v[18:19], v[214:215], 2, s[14:15]
	s_waitcnt lgkmcnt(0)
	v_add_f32_e32 v16, v16, v17
	global_atomic_add_f32 v[18:19], v16, off
.LBB0_238:
	s_or_b64 exec, exec, s[24:25]
	s_waitcnt lgkmcnt(0)
	v_lshl_add_u64 v[16:17], v[140:141], 2, v[212:213]
	v_lshl_add_u64 v[18:19], v[16:17], 0, s[20:21]
	v_add_co_u32_e32 v16, vcc, 0x120000, v16
	v_lshlrev_b64 v[20:21], 11, v[196:197]
	s_nop 0
	v_addc_co_u32_e32 v17, vcc, 0, v17, vcc
	global_load_dwordx4 v[44:47], v[18:19], off offset:64
	global_load_dwordx4 v[32:35], v[18:19], off offset:512
	global_load_dwordx4 v[56:59], v[16:17], off
	s_nop 0
	global_load_dwordx4 v[16:19], v[18:19], off offset:576
	v_lshl_add_u64 v[164:165], v[20:21], 0, v[140:141]
	s_waitcnt vmcnt(27)
	v_pk_add_f32 v[22:23], v[160:161], v[62:63]
	v_pk_add_f32 v[20:21], v[158:159], v[60:61]
	v_readlane_b32 s60, v252, 16
	v_readlane_b32 s74, v252, 30
	v_readlane_b32 s75, v252, 31
	v_mul_f32_e32 v62, v21, v21
	v_mul_f32_e32 v63, v23, v23
	v_lshl_add_u64 v[60:61], v[164:165], 2, s[74:75]
	v_fmac_f32_e32 v62, v20, v20
	v_fmac_f32_e32 v63, v22, v22
	global_store_dwordx4 v[60:61], v[20:23], off nt
	v_add_f32_e32 v158, v62, v63
	v_lshlrev_b64 v[62:63], 1, v[164:165]
	v_pk_mul_f32 v[22:23], v[14:15], v[22:23]
	v_pk_mul_f32 v[20:21], v[12:13], v[20:21]
	v_readlane_b32 s61, v252, 17
	v_cvt_pk_bf16_f32 v20, v20, v21
	v_cvt_pk_bf16_f32 v21, v22, v23
	v_lshl_add_u64 v[22:23], s[12:13], 0, v[62:63]
	global_store_dwordx2 v[22:23], v[20:21], off
	s_waitcnt vmcnt(28)
	v_pk_add_f32 v[22:23], v[156:157], v[54:55]
	v_pk_add_f32 v[20:21], v[154:155], v[52:53]
	v_mul_f32_e32 v53, v23, v23
	v_mul_f32_e32 v52, v21, v21
	global_store_dwordx4 v[60:61], v[20:23], off offset:64 nt
	v_fmac_f32_e32 v52, v20, v20
	v_fmac_f32_e32 v53, v22, v22
	v_pk_mul_f32 v[22:23], v[10:11], v[22:23]
	v_pk_mul_f32 v[20:21], v[8:9], v[20:21]
	v_add_f32_e32 v52, v52, v53
	v_cvt_pk_bf16_f32 v20, v20, v21
	v_cvt_pk_bf16_f32 v21, v22, v23
	v_or_b32_e32 v22, 32, v62
	v_mov_b32_e32 v23, v63
	v_lshl_add_u64 v[22:23], s[12:13], 0, v[22:23]
	global_store_dwordx2 v[22:23], v[20:21], off
	s_waitcnt vmcnt(29)
	v_pk_add_f32 v[22:23], v[152:153], v[42:43]
	v_pk_add_f32 v[20:21], v[150:151], v[40:41]
	v_mul_f32_e32 v41, v23, v23
	v_mul_f32_e32 v40, v21, v21
	global_store_dwordx4 v[60:61], v[20:23], off offset:512 nt
	v_fmac_f32_e32 v40, v20, v20
	v_fmac_f32_e32 v41, v22, v22
	v_pk_mul_f32 v[22:23], v[6:7], v[22:23]
	v_pk_mul_f32 v[20:21], v[4:5], v[20:21]
	v_add_f32_e32 v52, v158, v52
	v_cvt_pk_bf16_f32 v20, v20, v21
	v_cvt_pk_bf16_f32 v21, v22, v23
	v_or_b32_e32 v22, 0x100, v62
	v_mov_b32_e32 v23, v63
	v_lshl_add_u64 v[22:23], s[12:13], 0, v[22:23]
	global_store_dwordx2 v[22:23], v[20:21], off
	s_waitcnt vmcnt(30)
	v_pk_add_f32 v[22:23], v[148:149], v[30:31]
	v_pk_add_f32 v[20:21], v[146:147], v[28:29]
	v_mul_f32_e32 v29, v23, v23
	v_mul_f32_e32 v28, v21, v21
	v_add_f32_e32 v40, v40, v41
	v_fmac_f32_e32 v28, v20, v20
	v_fmac_f32_e32 v29, v22, v22
	v_add_f32_e32 v40, v52, v40
	v_add_f32_e32 v28, v28, v29
	v_add_f32_e32 v29, v40, v28
	ds_bpermute_b32 v30, v225, v29
	global_store_dwordx4 v[60:61], v[20:23], off offset:576 nt
	v_or_b32_e32 v62, 0x120, v62
	v_readlane_b32 s62, v252, 18
	v_pk_mul_f32 v[20:21], v[0:1], v[20:21]
	v_pk_mul_f32 v[22:23], v[2:3], v[22:23]
	v_cvt_pk_bf16_f32 v28, v20, v21
	s_waitcnt lgkmcnt(0)
	v_add_f32_e32 v20, v29, v30
	ds_bpermute_b32 v21, v224, v20
	v_cvt_pk_bf16_f32 v29, v22, v23
	v_lshl_add_u64 v[22:23], s[12:13], 0, v[62:63]
	v_readlane_b32 s63, v252, 19
	v_readlane_b32 s64, v252, 20
	v_readlane_b32 s65, v252, 21
	v_readlane_b32 s66, v252, 22
	v_readlane_b32 s67, v252, 23
	v_readlane_b32 s68, v252, 24
	v_readlane_b32 s69, v252, 25
	v_readlane_b32 s70, v252, 26
	v_readlane_b32 s71, v252, 27
	v_readlane_b32 s72, v252, 28
	v_readlane_b32 s73, v252, 29
	global_store_dwordx2 v[22:23], v[28:29], off
	s_and_saveexec_b64 s[24:25], s[4:5]
	s_cbranch_execz .LBB0_240
	v_lshl_add_u64 v[22:23], v[196:197], 2, s[14:15]
	s_waitcnt lgkmcnt(0)
	v_add_f32_e32 v20, v20, v21
	global_atomic_add_f32 v[22:23], v20, off
.LBB0_240:
	s_or_b64 exec, exec, s[24:25]
	v_or_b32_e32 v146, 32, v180
	v_ashrrev_i32_e32 v147, 31, v146
	v_readlane_b32 s60, v252, 0
	s_waitcnt lgkmcnt(0)
	v_lshlrev_b64 v[20:21], 13, v[146:147]
	v_readlane_b32 s61, v252, 1
	v_readlane_b32 s62, v252, 2
	v_readlane_b32 s63, v252, 3
	v_lshl_add_u64 v[20:21], s[60:61], 0, v[20:21]
	v_lshl_add_u64 v[20:21], v[140:141], 2, v[20:21]
	global_load_dwordx4 v[52:55], v[20:21], off
	global_load_dwordx4 v[40:43], v[20:21], off offset:64
	global_load_dwordx4 v[28:31], v[20:21], off offset:512
	s_nop 0
	global_load_dwordx4 v[20:23], v[20:21], off offset:576
	v_readlane_b32 s64, v252, 4
	v_readlane_b32 s65, v252, 5
	v_readlane_b32 s66, v252, 6
	v_readlane_b32 s67, v252, 7
	v_readlane_b32 s68, v252, 8
	v_readlane_b32 s69, v252, 9
	v_readlane_b32 s70, v252, 10
	v_readlane_b32 s71, v252, 11
	v_readlane_b32 s72, v252, 12
	v_readlane_b32 s73, v252, 13
	v_readlane_b32 s74, v252, 14
	v_readlane_b32 s75, v252, 15
	v_lshlrev_b64 v[60:61], 11, v[180:181]
	v_readlane_b32 s60, v252, 16
	v_lshl_add_u64 v[148:149], v[60:61], 0, v[140:141]
	s_waitcnt vmcnt(27)
	v_pk_add_f32 v[62:63], v[144:145], v[66:67]
	v_pk_add_f32 v[60:61], v[142:143], v[64:65]
	v_readlane_b32 s74, v252, 30
	v_readlane_b32 s75, v252, 31
	v_mul_f32_e32 v66, v61, v61
	v_mul_f32_e32 v67, v63, v63
	v_lshl_add_u64 v[64:65], v[148:149], 2, s[74:75]
	global_store_dwordx4 v[64:65], v[60:63], off nt
	v_fmac_f32_e32 v66, v60, v60
	v_fmac_f32_e32 v67, v62, v62
	v_pk_mul_f32 v[62:63], v[14:15], v[62:63]
	v_pk_mul_f32 v[60:61], v[12:13], v[60:61]
	v_add_f32_e32 v142, v66, v67
	v_cvt_pk_bf16_f32 v60, v60, v61
	v_cvt_pk_bf16_f32 v61, v62, v63
	v_lshlrev_b64 v[62:63], 1, v[148:149]
	v_lshl_add_u64 v[66:67], s[12:13], 0, v[62:63]
	s_waitcnt vmcnt(27)
	v_pk_add_f32 v[50:51], v[126:127], v[50:51]
	v_pk_add_f32 v[48:49], v[124:125], v[48:49]
	global_store_dwordx2 v[66:67], v[60:61], off
	v_mul_f32_e32 v60, v49, v49
	v_mul_f32_e32 v61, v51, v51
	global_store_dwordx4 v[64:65], v[48:51], off offset:64 nt
	v_fmac_f32_e32 v60, v48, v48
	v_fmac_f32_e32 v61, v50, v50
	v_pk_mul_f32 v[50:51], v[10:11], v[50:51]
	v_pk_mul_f32 v[48:49], v[8:9], v[48:49]
	s_waitcnt vmcnt(28)
	v_pk_add_f32 v[38:39], v[122:123], v[38:39]
	v_cvt_pk_bf16_f32 v48, v48, v49
	v_cvt_pk_bf16_f32 v49, v50, v51
	v_or_b32_e32 v50, 32, v62
	v_mov_b32_e32 v51, v63
	v_lshl_add_u64 v[50:51], s[12:13], 0, v[50:51]
	v_pk_add_f32 v[36:37], v[120:121], v[36:37]
	global_store_dwordx2 v[50:51], v[48:49], off
	v_mul_f32_e32 v48, v37, v37
	v_mul_f32_e32 v49, v39, v39
	global_store_dwordx4 v[64:65], v[36:39], off offset:512 nt
	v_fmac_f32_e32 v48, v36, v36
	v_fmac_f32_e32 v49, v38, v38
	v_pk_mul_f32 v[38:39], v[6:7], v[38:39]
	v_pk_mul_f32 v[36:37], v[4:5], v[36:37]
	s_waitcnt vmcnt(29)
	v_pk_add_f32 v[26:27], v[118:119], v[26:27]
	v_cvt_pk_bf16_f32 v36, v36, v37
	v_cvt_pk_bf16_f32 v37, v38, v39
	v_or_b32_e32 v38, 0x100, v62
	v_mov_b32_e32 v39, v63
	v_lshl_add_u64 v[38:39], s[12:13], 0, v[38:39]
	v_pk_add_f32 v[24:25], v[116:117], v[24:25]
	v_add_f32_e32 v60, v60, v61
	global_store_dwordx2 v[38:39], v[36:37], off
	v_mul_f32_e32 v36, v25, v25
	v_mul_f32_e32 v37, v27, v27
	v_add_f32_e32 v60, v142, v60
	v_add_f32_e32 v48, v48, v49
	v_fmac_f32_e32 v36, v24, v24
	v_fmac_f32_e32 v37, v26, v26
	v_add_f32_e32 v48, v60, v48
	v_add_f32_e32 v36, v36, v37
	v_add_f32_e32 v37, v48, v36
	ds_bpermute_b32 v38, v225, v37
	global_store_dwordx4 v[64:65], v[24:27], off offset:576 nt
	v_or_b32_e32 v62, 0x120, v62
	v_readlane_b32 s61, v252, 17
	v_pk_mul_f32 v[24:25], v[0:1], v[24:25]
	v_pk_mul_f32 v[26:27], v[2:3], v[26:27]
	v_cvt_pk_bf16_f32 v36, v24, v25
	s_waitcnt lgkmcnt(0)
	v_add_f32_e32 v24, v37, v38
	ds_bpermute_b32 v25, v224, v24
	v_cvt_pk_bf16_f32 v37, v26, v27
	v_lshl_add_u64 v[26:27], s[12:13], 0, v[62:63]
	v_readlane_b32 s62, v252, 18
	v_readlane_b32 s63, v252, 19
	v_readlane_b32 s64, v252, 20
	v_readlane_b32 s65, v252, 21
	v_readlane_b32 s66, v252, 22
	v_readlane_b32 s67, v252, 23
	v_readlane_b32 s68, v252, 24
	v_readlane_b32 s69, v252, 25
	v_readlane_b32 s70, v252, 26
	v_readlane_b32 s71, v252, 27
	v_readlane_b32 s72, v252, 28
	v_readlane_b32 s73, v252, 29
	global_store_dwordx2 v[26:27], v[36:37], off
	s_and_saveexec_b64 s[24:25], s[4:5]
	s_cbranch_execz .LBB0_242
	v_lshl_add_u64 v[26:27], v[180:181], 2, s[14:15]
	s_waitcnt lgkmcnt(0)
	v_add_f32_e32 v24, v24, v25
	global_atomic_add_f32 v[26:27], v24, off
.LBB0_242:
	s_or_b64 exec, exec, s[24:25]
	v_or_b32_e32 v64, 48, v180
	v_ashrrev_i32_e32 v65, 31, v64
	v_readlane_b32 s60, v252, 0
	s_waitcnt lgkmcnt(0)
	v_lshlrev_b64 v[24:25], 13, v[64:65]
	v_readlane_b32 s61, v252, 1
	v_or_b32_e32 v66, 16, v180
	v_readlane_b32 s62, v252, 2
	v_lshl_add_u64 v[24:25], s[60:61], 0, v[24:25]
	v_lshl_add_u64 v[24:25], v[140:141], 2, v[24:25]
	global_load_dwordx4 v[60:63], v[24:25], off
	global_load_dwordx4 v[48:51], v[24:25], off offset:64
	global_load_dwordx4 v[36:39], v[24:25], off offset:512
	s_nop 0
	global_load_dwordx4 v[24:27], v[24:25], off offset:576
	v_readlane_b32 s63, v252, 3
	v_readlane_b32 s64, v252, 4
	v_readlane_b32 s65, v252, 5
	v_readlane_b32 s66, v252, 6
	v_readlane_b32 s67, v252, 7
	v_readlane_b32 s68, v252, 8
	v_readlane_b32 s69, v252, 9
	v_readlane_b32 s70, v252, 10
	v_readlane_b32 s71, v252, 11
	v_readlane_b32 s72, v252, 12
	v_readlane_b32 s73, v252, 13
	v_readlane_b32 s74, v252, 14
	v_readlane_b32 s75, v252, 15
	v_ashrrev_i32_e32 v67, 31, v66
	v_lshlrev_b64 v[116:117], 11, v[66:67]
	v_readlane_b32 s60, v252, 16
	v_lshl_add_u64 v[116:117], v[116:117], 0, v[140:141]
	s_waitcnt vmcnt(25)
	v_pk_add_f32 v[58:59], v[114:115], v[58:59]
	v_pk_add_f32 v[56:57], v[112:113], v[56:57]
	v_readlane_b32 s74, v252, 30
	v_readlane_b32 s75, v252, 31
	v_mul_f32_e32 v114, v57, v57
	v_mul_f32_e32 v115, v59, v59
	v_lshl_add_u64 v[112:113], v[116:117], 2, s[74:75]
	global_store_dwordx4 v[112:113], v[56:59], off nt
	v_fmac_f32_e32 v114, v56, v56
	v_fmac_f32_e32 v115, v58, v58
	v_pk_mul_f32 v[58:59], v[14:15], v[58:59]
	v_pk_mul_f32 v[56:57], v[12:13], v[56:57]
	v_add_f32_e32 v118, v114, v115
	v_cvt_pk_bf16_f32 v56, v56, v57
	v_cvt_pk_bf16_f32 v57, v58, v59
	v_lshlrev_b64 v[58:59], 1, v[116:117]
	v_lshl_add_u64 v[114:115], s[12:13], 0, v[58:59]
	v_pk_add_f32 v[46:47], v[110:111], v[46:47]
	v_pk_add_f32 v[44:45], v[108:109], v[44:45]
	global_store_dwordx2 v[114:115], v[56:57], off
	v_mul_f32_e32 v56, v45, v45
	v_mul_f32_e32 v57, v47, v47
	global_store_dwordx4 v[112:113], v[44:47], off offset:64 nt
	v_fmac_f32_e32 v56, v44, v44
	v_fmac_f32_e32 v57, v46, v46
	v_pk_mul_f32 v[46:47], v[10:11], v[46:47]
	v_pk_mul_f32 v[44:45], v[8:9], v[44:45]
	v_pk_add_f32 v[34:35], v[106:107], v[34:35]
	v_cvt_pk_bf16_f32 v44, v44, v45
	v_cvt_pk_bf16_f32 v45, v46, v47
	v_or_b32_e32 v46, 32, v58
	v_mov_b32_e32 v47, v59
	v_lshl_add_u64 v[46:47], s[12:13], 0, v[46:47]
	v_pk_add_f32 v[32:33], v[104:105], v[32:33]
	global_store_dwordx2 v[46:47], v[44:45], off
	v_mul_f32_e32 v44, v33, v33
	v_mul_f32_e32 v45, v35, v35
	global_store_dwordx4 v[112:113], v[32:35], off offset:512 nt
	v_fmac_f32_e32 v44, v32, v32
	v_fmac_f32_e32 v45, v34, v34
	v_pk_mul_f32 v[34:35], v[6:7], v[34:35]
	v_pk_mul_f32 v[32:33], v[4:5], v[32:33]
	s_waitcnt vmcnt(29)
	v_pk_add_f32 v[18:19], v[102:103], v[18:19]
	v_cvt_pk_bf16_f32 v32, v32, v33
	v_cvt_pk_bf16_f32 v33, v34, v35
	v_or_b32_e32 v34, 0x100, v58
	v_mov_b32_e32 v35, v59
	v_lshl_add_u64 v[34:35], s[12:13], 0, v[34:35]
	v_pk_add_f32 v[16:17], v[100:101], v[16:17]
	v_add_f32_e32 v56, v56, v57
	global_store_dwordx2 v[34:35], v[32:33], off
	v_mul_f32_e32 v32, v17, v17
	v_mul_f32_e32 v33, v19, v19
	v_add_f32_e32 v56, v118, v56
	v_add_f32_e32 v44, v44, v45
	v_fmac_f32_e32 v32, v16, v16
	v_fmac_f32_e32 v33, v18, v18
	v_add_f32_e32 v44, v56, v44
	v_add_f32_e32 v32, v32, v33
	v_add_f32_e32 v33, v44, v32
	ds_bpermute_b32 v34, v225, v33
	global_store_dwordx4 v[112:113], v[16:19], off offset:576 nt
	v_or_b32_e32 v58, 0x120, v58
	v_readlane_b32 s61, v252, 17
	v_pk_mul_f32 v[16:17], v[0:1], v[16:17]
	v_pk_mul_f32 v[18:19], v[2:3], v[18:19]
	v_cvt_pk_bf16_f32 v32, v16, v17
	s_waitcnt lgkmcnt(0)
	v_add_f32_e32 v16, v33, v34
	ds_bpermute_b32 v17, v224, v16
	v_cvt_pk_bf16_f32 v33, v18, v19
	v_lshl_add_u64 v[18:19], s[12:13], 0, v[58:59]
	v_readlane_b32 s62, v252, 18
	v_readlane_b32 s63, v252, 19
	v_readlane_b32 s64, v252, 20
	v_readlane_b32 s65, v252, 21
	v_readlane_b32 s66, v252, 22
	v_readlane_b32 s67, v252, 23
	v_readlane_b32 s68, v252, 24
	v_readlane_b32 s69, v252, 25
	v_readlane_b32 s70, v252, 26
	v_readlane_b32 s71, v252, 27
	v_readlane_b32 s72, v252, 28
	v_readlane_b32 s73, v252, 29
	global_store_dwordx2 v[18:19], v[32:33], off
	s_and_saveexec_b64 s[24:25], s[4:5]
	s_cbranch_execz .LBB0_244
	v_lshl_add_u64 v[18:19], v[66:67], 2, s[14:15]
	s_waitcnt lgkmcnt(0)
	v_add_f32_e32 v16, v16, v17
	global_atomic_add_f32 v[18:19], v16, off
.LBB0_244:
	s_or_b64 exec, exec, s[24:25]
	s_waitcnt lgkmcnt(0)
	v_lshlrev_b64 v[16:17], 11, v[146:147]
	v_readlane_b32 s60, v252, 16
	v_lshl_add_u64 v[32:33], v[16:17], 0, v[140:141]
	s_waitcnt vmcnt(23)
	v_pk_add_f32 v[18:19], v[98:99], v[54:55]
	v_pk_add_f32 v[16:17], v[96:97], v[52:53]
	v_readlane_b32 s74, v252, 30
	v_readlane_b32 s75, v252, 31
	v_mul_f32_e32 v44, v17, v17
	v_mul_f32_e32 v45, v19, v19
	v_lshl_add_u64 v[34:35], v[32:33], 2, s[74:75]
	global_store_dwordx4 v[34:35], v[16:19], off nt
	v_fmac_f32_e32 v44, v16, v16
	v_fmac_f32_e32 v45, v18, v18
	v_pk_mul_f32 v[18:19], v[14:15], v[18:19]
	v_pk_mul_f32 v[16:17], v[12:13], v[16:17]
	v_lshlrev_b64 v[32:33], 1, v[32:33]
	v_cvt_pk_bf16_f32 v16, v16, v17
	v_cvt_pk_bf16_f32 v17, v18, v19
	v_lshl_add_u64 v[18:19], s[12:13], 0, v[32:33]
	global_store_dwordx2 v[18:19], v[16:17], off
	s_waitcnt vmcnt(24)
	v_pk_add_f32 v[18:19], v[94:95], v[42:43]
	v_pk_add_f32 v[16:17], v[92:93], v[40:41]
	v_mul_f32_e32 v41, v19, v19
	v_mul_f32_e32 v40, v17, v17
	global_store_dwordx4 v[34:35], v[16:19], off offset:64 nt
	v_fmac_f32_e32 v40, v16, v16
	v_fmac_f32_e32 v41, v18, v18
	v_pk_mul_f32 v[18:19], v[10:11], v[18:19]
	v_pk_mul_f32 v[16:17], v[8:9], v[16:17]
	v_add_f32_e32 v44, v44, v45
	v_cvt_pk_bf16_f32 v16, v16, v17
	v_cvt_pk_bf16_f32 v17, v18, v19
	v_or_b32_e32 v18, 32, v32
	v_mov_b32_e32 v19, v33
	v_lshl_add_u64 v[18:19], s[12:13], 0, v[18:19]
	global_store_dwordx2 v[18:19], v[16:17], off
	s_waitcnt vmcnt(25)
	v_pk_add_f32 v[18:19], v[90:91], v[30:31]
	v_pk_add_f32 v[16:17], v[88:89], v[28:29]
	v_mul_f32_e32 v29, v19, v19
	v_mul_f32_e32 v28, v17, v17
	global_store_dwordx4 v[34:35], v[16:19], off offset:512 nt
	v_fmac_f32_e32 v28, v16, v16
	v_fmac_f32_e32 v29, v18, v18
	v_pk_mul_f32 v[18:19], v[6:7], v[18:19]
	v_pk_mul_f32 v[16:17], v[4:5], v[16:17]
	v_add_f32_e32 v40, v40, v41
	v_cvt_pk_bf16_f32 v16, v16, v17
	v_cvt_pk_bf16_f32 v17, v18, v19
	v_or_b32_e32 v18, 0x100, v32
	v_mov_b32_e32 v19, v33
	v_lshl_add_u64 v[18:19], s[12:13], 0, v[18:19]
	global_store_dwordx2 v[18:19], v[16:17], off
	s_waitcnt vmcnt(26)
	v_pk_add_f32 v[18:19], v[86:87], v[22:23]
	v_pk_add_f32 v[16:17], v[84:85], v[20:21]
	v_mul_f32_e32 v21, v19, v19
	v_mul_f32_e32 v20, v17, v17
	v_add_f32_e32 v40, v44, v40
	v_add_f32_e32 v28, v28, v29
	v_fmac_f32_e32 v20, v16, v16
	v_fmac_f32_e32 v21, v18, v18
	v_add_f32_e32 v28, v40, v28
	v_add_f32_e32 v20, v20, v21
	v_add_f32_e32 v21, v28, v20
	ds_bpermute_b32 v22, v225, v21
	global_store_dwordx4 v[34:35], v[16:19], off offset:576 nt
	v_or_b32_e32 v32, 0x120, v32
	v_readlane_b32 s61, v252, 17
	v_pk_mul_f32 v[16:17], v[0:1], v[16:17]
	v_pk_mul_f32 v[18:19], v[2:3], v[18:19]
	v_cvt_pk_bf16_f32 v20, v16, v17
	s_waitcnt lgkmcnt(0)
	v_add_f32_e32 v16, v21, v22
	ds_bpermute_b32 v17, v224, v16
	v_cvt_pk_bf16_f32 v21, v18, v19
	v_lshl_add_u64 v[18:19], s[12:13], 0, v[32:33]
	v_readlane_b32 s62, v252, 18
	v_readlane_b32 s63, v252, 19
	v_readlane_b32 s64, v252, 20
	v_readlane_b32 s65, v252, 21
	v_readlane_b32 s66, v252, 22
	v_readlane_b32 s67, v252, 23
	v_readlane_b32 s68, v252, 24
	v_readlane_b32 s69, v252, 25
	v_readlane_b32 s70, v252, 26
	v_readlane_b32 s71, v252, 27
	v_readlane_b32 s72, v252, 28
	v_readlane_b32 s73, v252, 29
	global_store_dwordx2 v[18:19], v[20:21], off
	s_and_saveexec_b64 s[24:25], s[4:5]
	s_cbranch_execz .LBB0_246
	v_lshl_add_u64 v[18:19], v[146:147], 2, s[14:15]
	s_waitcnt lgkmcnt(0)
	v_add_f32_e32 v16, v16, v17
	global_atomic_add_f32 v[18:19], v16, off
.LBB0_246:
	s_or_b64 exec, exec, s[24:25]
	s_waitcnt lgkmcnt(0)
	v_lshlrev_b64 v[16:17], 11, v[64:65]
	v_readlane_b32 s60, v252, 16
	v_lshl_add_u64 v[20:21], v[16:17], 0, v[140:141]
	s_waitcnt vmcnt(19)
	v_pk_add_f32 v[16:17], v[80:81], v[60:61]
	v_readlane_b32 s74, v252, 30
	v_readlane_b32 s75, v252, 31
	v_pk_add_f32 v[18:19], v[82:83], v[62:63]
	v_mul_f32_e32 v28, v17, v17
	v_lshl_add_u64 v[22:23], v[20:21], 2, s[74:75]
	global_store_dwordx4 v[22:23], v[16:19], off nt
	v_fmac_f32_e32 v28, v16, v16
	v_pk_mul_f32 v[14:15], v[14:15], v[18:19]
	v_pk_mul_f32 v[12:13], v[12:13], v[16:17]
	v_lshlrev_b64 v[16:17], 1, v[20:21]
	v_cvt_pk_bf16_f32 v12, v12, v13
	v_cvt_pk_bf16_f32 v13, v14, v15
	v_lshl_add_u64 v[14:15], s[12:13], 0, v[16:17]
	global_store_dwordx2 v[14:15], v[12:13], off
	s_waitcnt vmcnt(20)
	v_pk_add_f32 v[14:15], v[78:79], v[50:51]
	v_pk_add_f32 v[12:13], v[76:77], v[48:49]
	v_pk_mul_f32 v[10:11], v[10:11], v[14:15]
	v_pk_mul_f32 v[8:9], v[8:9], v[12:13]
	global_store_dwordx4 v[22:23], v[12:15], off offset:64 nt
	v_cvt_pk_bf16_f32 v8, v8, v9
	v_cvt_pk_bf16_f32 v9, v10, v11
	v_or_b32_e32 v10, 32, v16
	v_mov_b32_e32 v11, v17
	v_lshl_add_u64 v[10:11], s[12:13], 0, v[10:11]
	global_store_dwordx2 v[10:11], v[8:9], off
	s_waitcnt vmcnt(21)
	v_pk_add_f32 v[10:11], v[74:75], v[38:39]
	v_pk_add_f32 v[8:9], v[72:73], v[36:37]
	v_pk_mul_f32 v[6:7], v[6:7], v[10:11]
	v_pk_mul_f32 v[4:5], v[4:5], v[8:9]
	v_mul_f32_e32 v29, v19, v19
	v_cvt_pk_bf16_f32 v4, v4, v5
	v_cvt_pk_bf16_f32 v5, v6, v7
	v_or_b32_e32 v6, 0x100, v16
	v_mov_b32_e32 v7, v17
	v_fmac_f32_e32 v29, v18, v18
	v_mul_f32_e32 v18, v13, v13
	v_mul_f32_e32 v19, v15, v15
	v_lshl_add_u64 v[6:7], s[12:13], 0, v[6:7]
	v_fmac_f32_e32 v18, v12, v12
	v_fmac_f32_e32 v19, v14, v14
	global_store_dwordx4 v[22:23], v[8:11], off offset:512 nt
	v_mul_f32_e32 v12, v9, v9
	v_mul_f32_e32 v13, v11, v11
	global_store_dwordx2 v[6:7], v[4:5], off
	s_waitcnt vmcnt(22)
	v_pk_add_f32 v[6:7], v[70:71], v[26:27]
	v_pk_add_f32 v[4:5], v[68:69], v[24:25]
	v_add_f32_e32 v28, v28, v29
	v_add_f32_e32 v18, v18, v19
	v_fmac_f32_e32 v12, v8, v8
	v_fmac_f32_e32 v13, v10, v10
	v_mul_f32_e32 v8, v5, v5
	v_mul_f32_e32 v9, v7, v7
	v_add_f32_e32 v18, v28, v18
	v_add_f32_e32 v12, v12, v13
	v_fmac_f32_e32 v8, v4, v4
	v_fmac_f32_e32 v9, v6, v6
	v_add_f32_e32 v12, v18, v12
	v_add_f32_e32 v8, v8, v9
	v_add_f32_e32 v8, v12, v8
	ds_bpermute_b32 v9, v225, v8
	v_pk_mul_f32 v[0:1], v[0:1], v[4:5]
	global_store_dwordx4 v[22:23], v[4:7], off offset:576 nt
	v_pk_mul_f32 v[2:3], v[2:3], v[6:7]
	v_or_b32_e32 v16, 0x120, v16
	v_cvt_pk_bf16_f32 v4, v0, v1
	s_waitcnt lgkmcnt(0)
	v_add_f32_e32 v0, v8, v9
	ds_bpermute_b32 v1, v224, v0
	v_cvt_pk_bf16_f32 v5, v2, v3
	v_lshl_add_u64 v[2:3], s[12:13], 0, v[16:17]
	v_readlane_b32 s61, v252, 17
	v_readlane_b32 s62, v252, 18
	v_readlane_b32 s63, v252, 19
	v_readlane_b32 s64, v252, 20
	v_readlane_b32 s65, v252, 21
	v_readlane_b32 s66, v252, 22
	v_readlane_b32 s67, v252, 23
	v_readlane_b32 s68, v252, 24
	v_readlane_b32 s69, v252, 25
	v_readlane_b32 s70, v252, 26
	v_readlane_b32 s71, v252, 27
	v_readlane_b32 s72, v252, 28
	v_readlane_b32 s73, v252, 29
	global_store_dwordx2 v[2:3], v[4:5], off
	s_and_saveexec_b64 s[24:25], s[4:5]
	s_cbranch_execz .LBB0_248
	v_lshl_add_u64 v[2:3], v[64:65], 2, s[14:15]
	s_waitcnt lgkmcnt(0)
	v_add_f32_e32 v0, v0, v1
	global_atomic_add_f32 v[2:3], v0, off

.LBB0_852:
	v_lshl_add_u32 v200, s54, 8, v206
	v_readlane_b32 s60, v252, 16
	v_lshl_or_b32 v188, s55, 8, v208
	v_ashrrev_i32_e32 v201, 31, v200
	v_readlane_b32 s74, v252, 30
	v_readlane_b32 s75, v252, 31
	v_ashrrev_i32_e32 v189, 31, v188
	v_lshlrev_b64 v[112:113], 13, v[200:201]
	v_readlane_b32 s72, v252, 28
	v_readlane_b32 s73, v252, 29
	s_mov_b64 s[82:83], s[74:75]
	v_lshlrev_b64 v[144:145], 2, v[188:189]
	v_readlane_b32 s61, v252, 17
	v_readlane_b32 s62, v252, 18
	v_readlane_b32 s63, v252, 19
	v_readlane_b32 s64, v252, 20
	v_readlane_b32 s65, v252, 21
	v_readlane_b32 s66, v252, 22
	v_readlane_b32 s67, v252, 23
	v_readlane_b32 s68, v252, 24
	v_readlane_b32 s69, v252, 25
	v_readlane_b32 s70, v252, 26
	v_readlane_b32 s71, v252, 27
	v_lshl_add_u64 v[190:191], s[82:83], 0, v[112:113]
	s_mov_b64 s[80:81], s[72:73]
	v_lshl_add_u64 v[230:231], v[190:191], 0, v[144:145]
	v_readlane_b32 s60, v252, 32
	global_load_dwordx4 v[196:199], v[230:231], off
	global_load_dwordx4 v[216:219], v[230:231], off offset:64
	global_load_dwordx4 v[222:225], v[230:231], off offset:512
	v_readlane_b32 s74, v252, 46
	v_readlane_b32 s75, v252, 47
	v_or_b32_e32 v202, 16, v200
	v_or_b32_e32 v192, 32, v200
	v_lshl_add_u64 v[112:113], s[74:75], 0, v[144:145]
	global_load_dwordx4 v[128:131], v[112:113], off
	global_load_dwordx4 v[120:123], v[112:113], off offset:64
	global_load_dwordx4 v[116:119], v[112:113], off offset:512
	global_load_dwordx4 v[226:229], v[230:231], off offset:576
	v_ashrrev_i32_e32 v203, 31, v202
	v_ashrrev_i32_e32 v193, 31, v192
	v_lshlrev_b64 v[146:147], 13, v[202:203]
	v_lshlrev_b64 v[148:149], 13, v[192:193]
	v_lshl_add_u64 v[146:147], s[82:83], 0, v[146:147]
	global_load_dwordx4 v[112:115], v[112:113], off offset:576
	v_lshl_add_u64 v[148:149], s[82:83], 0, v[148:149]
	v_lshl_add_u64 v[204:205], v[146:147], 0, v[144:145]
	v_lshl_add_u64 v[194:195], v[148:149], 0, v[144:145]
	global_load_dwordx4 v[172:175], v[204:205], off
	global_load_dwordx4 v[168:171], v[204:205], off offset:64
	global_load_dwordx4 v[164:167], v[204:205], off offset:512
	global_load_dwordx4 v[160:163], v[204:205], off offset:576
	global_load_dwordx4 v[156:159], v[194:195], off
	global_load_dwordx4 v[152:155], v[194:195], off offset:64
	global_load_dwordx4 v[148:151], v[194:195], off offset:512
	global_load_dwordx4 v[144:147], v[194:195], off offset:576
	v_and_b32_e32 v214, 64, v212
	v_xor_b32_e32 v213, 16, v212
	v_add_u32_e32 v214, 64, v214
	v_xor_b32_e32 v215, 32, v212
	v_cmp_lt_i32_e32 vcc, v213, v214
	v_lshlrev_b64 v[232:233], 11, v[200:201]
	v_lshl_add_u64 v[232:233], v[232:233], 0, v[188:189]
	v_cndmask_b32_e32 v213, v212, v213, vcc
	v_cmp_lt_i32_e32 vcc, v215, v214
	v_lshlrev_b32_e32 v214, 2, v213
	v_lshlrev_b64 v[232:233], 1, v[232:233]
	v_cndmask_b32_e32 v215, v212, v215, vcc
	v_lshlrev_b32_e32 v213, 2, v215
	v_lshl_add_u64 v[234:235], s[14:15], 0, v[232:233]
	v_or_b32_e32 v236, 32, v232
	v_mov_b32_e32 v237, v233
	v_lshl_add_u64 v[236:237], s[14:15], 0, v[236:237]
	v_readlane_b32 s61, v252, 33
	v_readlane_b32 s62, v252, 34
	v_readlane_b32 s63, v252, 35
	v_readlane_b32 s64, v252, 36
	v_readlane_b32 s65, v252, 37
	v_readlane_b32 s66, v252, 38
	v_readlane_b32 s67, v252, 39
	v_readlane_b32 s68, v252, 40
	v_readlane_b32 s69, v252, 41
	v_readlane_b32 s70, v252, 42
	v_readlane_b32 s71, v252, 43
	v_readlane_b32 s72, v252, 44
	v_readlane_b32 s73, v252, 45
	s_waitcnt vmcnt(0)
	v_pk_add_f32 v[138:139], v[138:139], v[198:199]
	v_pk_add_f32 v[136:137], v[136:137], v[196:197]
	v_pk_add_f32 v[142:143], v[142:143], v[218:219]
	v_pk_add_f32 v[140:141], v[140:141], v[216:217]
	v_pk_add_f32 v[134:135], v[134:135], v[224:225]
	v_pk_add_f32 v[132:133], v[132:133], v[222:223]
	v_mul_f32_e32 v215, v137, v137
	v_mul_f32_e32 v221, v139, v139
	v_pk_mul_f32 v[196:197], v[130:131], v[138:139]
	v_pk_mul_f32 v[198:199], v[128:129], v[136:137]
	v_mul_f32_e32 v238, v141, v141
	v_mul_f32_e32 v239, v143, v143
	global_store_dwordx4 v[230:231], v[136:139], off nt
	v_pk_mul_f32 v[216:217], v[122:123], v[142:143]
	v_pk_mul_f32 v[218:219], v[120:121], v[140:141]
	v_mul_f32_e32 v240, v133, v133
	v_mul_f32_e32 v241, v135, v135
	v_fmac_f32_e32 v215, v136, v136
	v_fmac_f32_e32 v221, v138, v138
	v_cvt_pk_bf16_f32 v136, v198, v199
	v_cvt_pk_bf16_f32 v137, v196, v197
	v_fmac_f32_e32 v238, v140, v140
	v_fmac_f32_e32 v239, v142, v142
	v_cvt_pk_bf16_f32 v138, v218, v219
	v_cvt_pk_bf16_f32 v139, v216, v217
	v_fmac_f32_e32 v240, v132, v132
	v_fmac_f32_e32 v241, v134, v134
	v_add_f32_e32 v197, v215, v221
	global_store_dwordx2 v[234:235], v[136:137], off
	global_store_dwordx4 v[230:231], v[140:143], off offset:64 nt
	v_add_f32_e32 v136, v238, v239
	v_pk_mul_f32 v[224:225], v[116:117], v[132:133]
	global_store_dwordx2 v[236:237], v[138:139], off
	global_store_dwordx4 v[230:231], v[132:135], off offset:512 nt
	v_pk_mul_f32 v[222:223], v[118:119], v[134:135]
	v_cvt_pk_bf16_f32 v196, v224, v225
	v_add_f32_e32 v132, v240, v241
	v_add_f32_e32 v133, v197, v136
	v_add_f32_e32 v134, v133, v132
	v_or_b32_e32 v132, 0x100, v232
	v_mov_b32_e32 v133, v233
	v_cvt_pk_bf16_f32 v197, v222, v223
	v_lshl_add_u64 v[132:133], s[14:15], 0, v[132:133]
	v_pk_add_f32 v[126:127], v[126:127], v[228:229]
	v_pk_add_f32 v[124:125], v[124:125], v[226:227]
	global_store_dwordx2 v[132:133], v[196:197], off
	v_mul_f32_e32 v132, v125, v125
	v_mul_f32_e32 v133, v127, v127
	v_fmac_f32_e32 v132, v124, v124
	v_fmac_f32_e32 v133, v126, v126
	v_add_f32_e32 v132, v132, v133
	v_add_f32_e32 v133, v134, v132
	ds_bpermute_b32 v134, v214, v133
	global_store_dwordx4 v[230:231], v[124:127], off offset:576 nt
	v_or_b32_e32 v232, 0x120, v232
	s_nop 0
	v_pk_mul_f32 v[124:125], v[112:113], v[124:125]
	v_pk_mul_f32 v[126:127], v[114:115], v[126:127]
	v_cvt_pk_bf16_f32 v132, v124, v125
	s_waitcnt lgkmcnt(0)
	v_add_f32_e32 v124, v133, v134
	ds_bpermute_b32 v125, v213, v124
	v_cvt_pk_bf16_f32 v133, v126, v127
	v_lshl_add_u64 v[126:127], s[14:15], 0, v[232:233]
	global_store_dwordx2 v[126:127], v[132:133], off
	s_and_saveexec_b64 s[28:29], s[2:3]
	s_cbranch_execz .LBB0_854
	v_lshl_add_u64 v[126:127], v[200:201], 2, s[16:17]
	s_waitcnt lgkmcnt(0)
	v_add_f32_e32 v124, v124, v125
	global_atomic_add_f32 v[126:127], v124, off
.LBB0_854:
	s_or_b64 exec, exec, s[28:29]
	v_or_b32_e32 v196, 48, v200
	v_ashrrev_i32_e32 v197, 31, v196
	v_readlane_b32 s60, v252, 16
	s_waitcnt lgkmcnt(0)
	v_lshlrev_b64 v[124:125], 13, v[196:197]
	v_readlane_b32 s74, v252, 30
	v_readlane_b32 s75, v252, 31
	v_pk_add_f32 v[110:111], v[110:111], v[174:175]
	v_pk_add_f32 v[108:109], v[108:109], v[172:173]
	v_lshl_add_u64 v[124:125], s[74:75], 0, v[124:125]
	v_lshl_add_u64 v[198:199], v[188:189], 2, v[124:125]
	global_load_dwordx4 v[140:143], v[198:199], off
	global_load_dwordx4 v[136:139], v[198:199], off offset:64
	global_load_dwordx4 v[132:135], v[198:199], off offset:512
	global_load_dwordx4 v[124:127], v[198:199], off offset:576
	v_lshlrev_b64 v[216:217], 11, v[202:203]
	v_mul_f32_e32 v172, v109, v109
	v_mul_f32_e32 v173, v111, v111
	v_lshl_add_u64 v[216:217], v[216:217], 0, v[188:189]
	global_store_dwordx4 v[204:205], v[108:111], off nt
	v_fmac_f32_e32 v172, v108, v108
	v_fmac_f32_e32 v173, v110, v110
	v_pk_mul_f32 v[110:111], v[130:131], v[110:111]
	v_pk_mul_f32 v[108:109], v[128:129], v[108:109]
	v_add_f32_e32 v174, v172, v173
	v_cvt_pk_bf16_f32 v108, v108, v109
	v_cvt_pk_bf16_f32 v109, v110, v111
	v_lshlrev_b64 v[110:111], 1, v[216:217]
	v_lshl_add_u64 v[172:173], s[14:15], 0, v[110:111]
	v_pk_add_f32 v[106:107], v[106:107], v[170:171]
	v_pk_add_f32 v[104:105], v[104:105], v[168:169]
	global_store_dwordx2 v[172:173], v[108:109], off
	v_mul_f32_e32 v108, v105, v105
	v_mul_f32_e32 v109, v107, v107
	global_store_dwordx4 v[204:205], v[104:107], off offset:64 nt
	v_fmac_f32_e32 v108, v104, v104
	v_fmac_f32_e32 v109, v106, v106
	v_pk_mul_f32 v[106:107], v[122:123], v[106:107]
	v_pk_mul_f32 v[104:105], v[120:121], v[104:105]
	v_pk_add_f32 v[102:103], v[102:103], v[166:167]
	v_cvt_pk_bf16_f32 v104, v104, v105
	v_cvt_pk_bf16_f32 v105, v106, v107
	v_or_b32_e32 v106, 32, v110
	v_mov_b32_e32 v107, v111
	v_lshl_add_u64 v[106:107], s[14:15], 0, v[106:107]
	v_pk_add_f32 v[100:101], v[100:101], v[164:165]
	global_store_dwordx2 v[106:107], v[104:105], off
	v_mul_f32_e32 v104, v101, v101
	v_mul_f32_e32 v105, v103, v103
	global_store_dwordx4 v[204:205], v[100:103], off offset:512 nt
	v_fmac_f32_e32 v104, v100, v100
	v_fmac_f32_e32 v105, v102, v102
	v_pk_mul_f32 v[102:103], v[118:119], v[102:103]
	v_pk_mul_f32 v[100:101], v[116:117], v[100:101]
	v_pk_add_f32 v[98:99], v[98:99], v[162:163]
	v_cvt_pk_bf16_f32 v100, v100, v101
	v_cvt_pk_bf16_f32 v101, v102, v103
	v_or_b32_e32 v102, 0x100, v110
	v_mov_b32_e32 v103, v111
	v_lshl_add_u64 v[102:103], s[14:15], 0, v[102:103]
	v_pk_add_f32 v[96:97], v[96:97], v[160:161]
	v_add_f32_e32 v108, v108, v109
	global_store_dwordx2 v[102:103], v[100:101], off
	v_mul_f32_e32 v100, v97, v97
	v_mul_f32_e32 v101, v99, v99
	v_add_f32_e32 v108, v174, v108
	v_add_f32_e32 v104, v104, v105
	v_fmac_f32_e32 v100, v96, v96
	v_fmac_f32_e32 v101, v98, v98
	v_add_f32_e32 v104, v108, v104
	v_add_f32_e32 v100, v100, v101
	v_add_f32_e32 v101, v104, v100
	ds_bpermute_b32 v102, v214, v101
	global_store_dwordx4 v[204:205], v[96:99], off offset:576 nt
	v_or_b32_e32 v110, 0x120, v110
	v_readlane_b32 s61, v252, 17
	v_pk_mul_f32 v[96:97], v[112:113], v[96:97]
	v_pk_mul_f32 v[98:99], v[114:115], v[98:99]
	v_cvt_pk_bf16_f32 v100, v96, v97
	s_waitcnt lgkmcnt(0)
	v_add_f32_e32 v96, v101, v102
	ds_bpermute_b32 v97, v213, v96
	v_cvt_pk_bf16_f32 v101, v98, v99
	v_lshl_add_u64 v[98:99], s[14:15], 0, v[110:111]
	v_readlane_b32 s62, v252, 18
	v_readlane_b32 s63, v252, 19
	v_readlane_b32 s64, v252, 20
	v_readlane_b32 s65, v252, 21
	v_readlane_b32 s66, v252, 22
	v_readlane_b32 s67, v252, 23
	v_readlane_b32 s68, v252, 24
	v_readlane_b32 s69, v252, 25
	v_readlane_b32 s70, v252, 26
	v_readlane_b32 s71, v252, 27
	v_readlane_b32 s72, v252, 28
	v_readlane_b32 s73, v252, 29
	global_store_dwordx2 v[98:99], v[100:101], off
	s_and_saveexec_b64 s[28:29], s[2:3]
	s_cbranch_execz .LBB0_856
	v_lshl_add_u64 v[98:99], v[202:203], 2, s[16:17]
	s_waitcnt lgkmcnt(0)
	v_add_f32_e32 v96, v96, v97
	global_atomic_add_f32 v[98:99], v96, off
.LBB0_856:
	s_or_b64 exec, exec, s[28:29]
	v_add_u32_e32 v160, 0x80, v200
	v_ashrrev_i32_e32 v161, 31, v160
	v_readlane_b32 s60, v252, 16
	s_waitcnt lgkmcnt(0)
	v_lshlrev_b64 v[96:97], 13, v[160:161]
	v_readlane_b32 s74, v252, 30
	v_readlane_b32 s75, v252, 31
	v_pk_add_f32 v[94:95], v[94:95], v[158:159]
	v_pk_add_f32 v[92:93], v[92:93], v[156:157]
	v_lshl_add_u64 v[96:97], s[74:75], 0, v[96:97]
	v_lshl_add_u64 v[162:163], v[188:189], 2, v[96:97]
	global_load_dwordx4 v[108:111], v[162:163], off
	global_load_dwordx4 v[104:107], v[162:163], off offset:64
	global_load_dwordx4 v[100:103], v[162:163], off offset:512
	global_load_dwordx4 v[96:99], v[162:163], off offset:576
	v_lshlrev_b64 v[164:165], 11, v[192:193]
	v_mul_f32_e32 v156, v93, v93
	v_mul_f32_e32 v157, v95, v95
	v_lshl_add_u64 v[164:165], v[164:165], 0, v[188:189]
	global_store_dwordx4 v[194:195], v[92:95], off nt
	v_fmac_f32_e32 v156, v92, v92
	v_fmac_f32_e32 v157, v94, v94
	v_pk_mul_f32 v[94:95], v[130:131], v[94:95]
	v_pk_mul_f32 v[92:93], v[128:129], v[92:93]
	v_add_f32_e32 v158, v156, v157
	v_cvt_pk_bf16_f32 v92, v92, v93
	v_cvt_pk_bf16_f32 v93, v94, v95
	v_lshlrev_b64 v[94:95], 1, v[164:165]
	v_lshl_add_u64 v[156:157], s[14:15], 0, v[94:95]
	v_pk_add_f32 v[90:91], v[90:91], v[154:155]
	v_pk_add_f32 v[88:89], v[88:89], v[152:153]
	global_store_dwordx2 v[156:157], v[92:93], off
	v_mul_f32_e32 v92, v89, v89
	v_mul_f32_e32 v93, v91, v91
	global_store_dwordx4 v[194:195], v[88:91], off offset:64 nt
	v_fmac_f32_e32 v92, v88, v88
	v_fmac_f32_e32 v93, v90, v90
	v_pk_mul_f32 v[90:91], v[122:123], v[90:91]
	v_pk_mul_f32 v[88:89], v[120:121], v[88:89]
	v_pk_add_f32 v[86:87], v[86:87], v[150:151]
	v_cvt_pk_bf16_f32 v88, v88, v89
	v_cvt_pk_bf16_f32 v89, v90, v91
	v_or_b32_e32 v90, 32, v94
	v_mov_b32_e32 v91, v95
	v_lshl_add_u64 v[90:91], s[14:15], 0, v[90:91]
	v_pk_add_f32 v[84:85], v[84:85], v[148:149]
	global_store_dwordx2 v[90:91], v[88:89], off
	v_mul_f32_e32 v88, v85, v85
	v_mul_f32_e32 v89, v87, v87
	global_store_dwordx4 v[194:195], v[84:87], off offset:512 nt
	v_fmac_f32_e32 v88, v84, v84
	v_fmac_f32_e32 v89, v86, v86
	v_pk_mul_f32 v[86:87], v[118:119], v[86:87]
	v_pk_mul_f32 v[84:85], v[116:117], v[84:85]
	v_pk_add_f32 v[82:83], v[82:83], v[146:147]
	v_cvt_pk_bf16_f32 v84, v84, v85
	v_cvt_pk_bf16_f32 v85, v86, v87
	v_or_b32_e32 v86, 0x100, v94
	v_mov_b32_e32 v87, v95
	v_lshl_add_u64 v[86:87], s[14:15], 0, v[86:87]
	v_pk_add_f32 v[80:81], v[80:81], v[144:145]
	v_add_f32_e32 v92, v92, v93
	global_store_dwordx2 v[86:87], v[84:85], off
	v_mul_f32_e32 v84, v81, v81
	v_mul_f32_e32 v85, v83, v83
	v_add_f32_e32 v92, v158, v92
	v_add_f32_e32 v88, v88, v89
	v_fmac_f32_e32 v84, v80, v80
	v_fmac_f32_e32 v85, v82, v82
	v_add_f32_e32 v88, v92, v88
	v_add_f32_e32 v84, v84, v85
	v_add_f32_e32 v85, v88, v84
	ds_bpermute_b32 v86, v214, v85
	global_store_dwordx4 v[194:195], v[80:83], off offset:576 nt
	v_or_b32_e32 v94, 0x120, v94
	v_readlane_b32 s61, v252, 17
	v_pk_mul_f32 v[80:81], v[112:113], v[80:81]
	v_pk_mul_f32 v[82:83], v[114:115], v[82:83]
	v_cvt_pk_bf16_f32 v84, v80, v81
	s_waitcnt lgkmcnt(0)
	v_add_f32_e32 v80, v85, v86
	ds_bpermute_b32 v81, v213, v80
	v_cvt_pk_bf16_f32 v85, v82, v83
	v_lshl_add_u64 v[82:83], s[14:15], 0, v[94:95]
	v_readlane_b32 s62, v252, 18
	v_readlane_b32 s63, v252, 19
	v_readlane_b32 s64, v252, 20
	v_readlane_b32 s65, v252, 21
	v_readlane_b32 s66, v252, 22
	v_readlane_b32 s67, v252, 23
	v_readlane_b32 s68, v252, 24
	v_readlane_b32 s69, v252, 25
	v_readlane_b32 s70, v252, 26
	v_readlane_b32 s71, v252, 27
	v_readlane_b32 s72, v252, 28
	v_readlane_b32 s73, v252, 29
	global_store_dwordx2 v[82:83], v[84:85], off
	s_and_saveexec_b64 s[28:29], s[2:3]
	s_cbranch_execz .LBB0_858
	v_lshl_add_u64 v[82:83], v[192:193], 2, s[16:17]
	s_waitcnt lgkmcnt(0)
	v_add_f32_e32 v80, v80, v81
	global_atomic_add_f32 v[82:83], v80, off
.LBB0_858:
	s_or_b64 exec, exec, s[28:29]
	s_waitcnt lgkmcnt(0)
	v_lshl_add_u64 v[80:81], v[188:189], 2, v[190:191]
	v_lshl_add_u64 v[144:145], v[80:81], 0, s[24:25]
	v_add_co_u32_e32 v80, vcc, 0x120000, v80
	s_waitcnt vmcnt(23)
	v_pk_add_f32 v[78:79], v[78:79], v[142:143]
	v_addc_co_u32_e32 v81, vcc, 0, v81, vcc
	global_load_dwordx4 v[88:91], v[144:145], off offset:64
	global_load_dwordx4 v[84:87], v[144:145], off offset:512
	global_load_dwordx4 v[92:95], v[80:81], off
	s_nop 0
	global_load_dwordx4 v[80:83], v[144:145], off offset:576
	v_pk_add_f32 v[76:77], v[76:77], v[140:141]
	v_lshlrev_b64 v[146:147], 11, v[196:197]
	v_mul_f32_e32 v140, v77, v77
	v_mul_f32_e32 v141, v79, v79
	v_lshl_add_u64 v[146:147], v[146:147], 0, v[188:189]
	global_store_dwordx4 v[198:199], v[76:79], off nt
	v_fmac_f32_e32 v140, v76, v76
	v_fmac_f32_e32 v141, v78, v78
	v_pk_mul_f32 v[78:79], v[130:131], v[78:79]
	v_pk_mul_f32 v[76:77], v[128:129], v[76:77]
	v_add_f32_e32 v142, v140, v141
	v_cvt_pk_bf16_f32 v76, v76, v77
	v_cvt_pk_bf16_f32 v77, v78, v79
	v_lshlrev_b64 v[78:79], 1, v[146:147]
	v_lshl_add_u64 v[140:141], s[14:15], 0, v[78:79]
	s_waitcnt vmcnt(27)
	v_pk_add_f32 v[74:75], v[74:75], v[138:139]
	v_pk_add_f32 v[72:73], v[72:73], v[136:137]
	global_store_dwordx2 v[140:141], v[76:77], off
	v_mul_f32_e32 v76, v73, v73
	v_mul_f32_e32 v77, v75, v75
	global_store_dwordx4 v[198:199], v[72:75], off offset:64 nt
	v_fmac_f32_e32 v76, v72, v72
	v_fmac_f32_e32 v77, v74, v74
	v_pk_mul_f32 v[74:75], v[122:123], v[74:75]
	v_pk_mul_f32 v[72:73], v[120:121], v[72:73]
	s_waitcnt vmcnt(28)
	v_pk_add_f32 v[70:71], v[70:71], v[134:135]
	v_cvt_pk_bf16_f32 v72, v72, v73
	v_cvt_pk_bf16_f32 v73, v74, v75
	v_or_b32_e32 v74, 32, v78
	v_mov_b32_e32 v75, v79
	v_lshl_add_u64 v[74:75], s[14:15], 0, v[74:75]
	v_pk_add_f32 v[68:69], v[68:69], v[132:133]
	global_store_dwordx2 v[74:75], v[72:73], off
	v_mul_f32_e32 v72, v69, v69
	v_mul_f32_e32 v73, v71, v71
	global_store_dwordx4 v[198:199], v[68:71], off offset:512 nt
	v_fmac_f32_e32 v72, v68, v68
	v_fmac_f32_e32 v73, v70, v70
	v_pk_mul_f32 v[70:71], v[118:119], v[70:71]
	v_pk_mul_f32 v[68:69], v[116:117], v[68:69]
	s_waitcnt vmcnt(29)
	v_pk_add_f32 v[66:67], v[66:67], v[126:127]
	v_cvt_pk_bf16_f32 v68, v68, v69
	v_cvt_pk_bf16_f32 v69, v70, v71
	v_or_b32_e32 v70, 0x100, v78
	v_mov_b32_e32 v71, v79
	v_lshl_add_u64 v[70:71], s[14:15], 0, v[70:71]
	v_pk_add_f32 v[64:65], v[64:65], v[124:125]
	v_add_f32_e32 v76, v76, v77
	global_store_dwordx2 v[70:71], v[68:69], off
	v_mul_f32_e32 v68, v65, v65
	v_mul_f32_e32 v69, v67, v67
	v_add_f32_e32 v76, v142, v76
	v_add_f32_e32 v72, v72, v73
	v_fmac_f32_e32 v68, v64, v64
	v_fmac_f32_e32 v69, v66, v66
	v_add_f32_e32 v72, v76, v72
	v_add_f32_e32 v68, v68, v69
	v_add_f32_e32 v69, v72, v68
	ds_bpermute_b32 v70, v214, v69
	global_store_dwordx4 v[198:199], v[64:67], off offset:576 nt
	v_or_b32_e32 v78, 0x120, v78
	s_nop 0
	v_pk_mul_f32 v[64:65], v[112:113], v[64:65]
	v_pk_mul_f32 v[66:67], v[114:115], v[66:67]
	v_cvt_pk_bf16_f32 v68, v64, v65
	s_waitcnt lgkmcnt(0)
	v_add_f32_e32 v64, v69, v70
	ds_bpermute_b32 v65, v213, v64
	v_cvt_pk_bf16_f32 v69, v66, v67
	v_lshl_add_u64 v[66:67], s[14:15], 0, v[78:79]
	global_store_dwordx2 v[66:67], v[68:69], off
	s_and_saveexec_b64 s[28:29], s[2:3]
	s_cbranch_execz .LBB0_860
	v_lshl_add_u64 v[66:67], v[196:197], 2, s[16:17]
	s_waitcnt lgkmcnt(0)
	v_add_f32_e32 v64, v64, v65
	global_atomic_add_f32 v[66:67], v64, off
.LBB0_860:
	s_or_b64 exec, exec, s[28:29]
	v_or_b32_e32 v124, 32, v160
	v_ashrrev_i32_e32 v125, 31, v124
	v_readlane_b32 s60, v252, 16
	s_waitcnt lgkmcnt(0)
	v_lshlrev_b64 v[64:65], 13, v[124:125]
	v_readlane_b32 s74, v252, 30
	v_readlane_b32 s75, v252, 31
	s_waitcnt vmcnt(23)
	v_pk_add_f32 v[62:63], v[62:63], v[110:111]
	v_pk_add_f32 v[60:61], v[60:61], v[108:109]
	v_lshl_add_u64 v[64:65], s[74:75], 0, v[64:65]
	v_lshl_add_u64 v[126:127], v[188:189], 2, v[64:65]
	global_load_dwordx4 v[76:79], v[126:127], off
	global_load_dwordx4 v[72:75], v[126:127], off offset:64
	global_load_dwordx4 v[68:71], v[126:127], off offset:512
	global_load_dwordx4 v[64:67], v[126:127], off offset:576
	v_lshlrev_b64 v[132:133], 11, v[160:161]
	v_mul_f32_e32 v108, v61, v61
	v_mul_f32_e32 v109, v63, v63
	v_lshl_add_u64 v[132:133], v[132:133], 0, v[188:189]
	global_store_dwordx4 v[162:163], v[60:63], off nt
	v_fmac_f32_e32 v108, v60, v60
	v_fmac_f32_e32 v109, v62, v62
	v_pk_mul_f32 v[62:63], v[130:131], v[62:63]
	v_pk_mul_f32 v[60:61], v[128:129], v[60:61]
	v_add_f32_e32 v110, v108, v109
	v_cvt_pk_bf16_f32 v60, v60, v61
	v_cvt_pk_bf16_f32 v61, v62, v63
	v_lshlrev_b64 v[62:63], 1, v[132:133]
	v_lshl_add_u64 v[108:109], s[14:15], 0, v[62:63]
	s_waitcnt vmcnt(27)
	v_pk_add_f32 v[58:59], v[58:59], v[106:107]
	v_pk_add_f32 v[56:57], v[56:57], v[104:105]
	global_store_dwordx2 v[108:109], v[60:61], off
	v_mul_f32_e32 v60, v57, v57
	v_mul_f32_e32 v61, v59, v59
	global_store_dwordx4 v[162:163], v[56:59], off offset:64 nt
	v_fmac_f32_e32 v60, v56, v56
	v_fmac_f32_e32 v61, v58, v58
	v_pk_mul_f32 v[58:59], v[122:123], v[58:59]
	v_pk_mul_f32 v[56:57], v[120:121], v[56:57]
	s_waitcnt vmcnt(28)
	v_pk_add_f32 v[54:55], v[54:55], v[102:103]
	v_cvt_pk_bf16_f32 v56, v56, v57
	v_cvt_pk_bf16_f32 v57, v58, v59
	v_or_b32_e32 v58, 32, v62
	v_mov_b32_e32 v59, v63
	v_lshl_add_u64 v[58:59], s[14:15], 0, v[58:59]
	v_pk_add_f32 v[52:53], v[52:53], v[100:101]
	global_store_dwordx2 v[58:59], v[56:57], off
	v_mul_f32_e32 v56, v53, v53
	v_mul_f32_e32 v57, v55, v55
	global_store_dwordx4 v[162:163], v[52:55], off offset:512 nt
	v_fmac_f32_e32 v56, v52, v52
	v_fmac_f32_e32 v57, v54, v54
	v_pk_mul_f32 v[54:55], v[118:119], v[54:55]
	v_pk_mul_f32 v[52:53], v[116:117], v[52:53]
	s_waitcnt vmcnt(29)
	v_pk_add_f32 v[50:51], v[50:51], v[98:99]
	v_cvt_pk_bf16_f32 v52, v52, v53
	v_cvt_pk_bf16_f32 v53, v54, v55
	v_or_b32_e32 v54, 0x100, v62
	v_mov_b32_e32 v55, v63
	v_lshl_add_u64 v[54:55], s[14:15], 0, v[54:55]
	v_pk_add_f32 v[48:49], v[48:49], v[96:97]
	v_add_f32_e32 v60, v60, v61
	global_store_dwordx2 v[54:55], v[52:53], off
	v_mul_f32_e32 v52, v49, v49
	v_mul_f32_e32 v53, v51, v51
	v_add_f32_e32 v60, v110, v60
	v_add_f32_e32 v56, v56, v57
	v_fmac_f32_e32 v52, v48, v48
	v_fmac_f32_e32 v53, v50, v50
	v_add_f32_e32 v56, v60, v56
	v_add_f32_e32 v52, v52, v53
	v_add_f32_e32 v53, v56, v52
	ds_bpermute_b32 v54, v214, v53
	global_store_dwordx4 v[162:163], v[48:51], off offset:576 nt
	v_or_b32_e32 v62, 0x120, v62
	v_readlane_b32 s61, v252, 17
	v_pk_mul_f32 v[48:49], v[112:113], v[48:49]
	v_pk_mul_f32 v[50:51], v[114:115], v[50:51]
	v_cvt_pk_bf16_f32 v52, v48, v49
	s_waitcnt lgkmcnt(0)
	v_add_f32_e32 v48, v53, v54
	ds_bpermute_b32 v49, v213, v48
	v_cvt_pk_bf16_f32 v53, v50, v51
	v_lshl_add_u64 v[50:51], s[14:15], 0, v[62:63]
	v_readlane_b32 s62, v252, 18
	v_readlane_b32 s63, v252, 19
	v_readlane_b32 s64, v252, 20
	v_readlane_b32 s65, v252, 21
	v_readlane_b32 s66, v252, 22
	v_readlane_b32 s67, v252, 23
	v_readlane_b32 s68, v252, 24
	v_readlane_b32 s69, v252, 25
	v_readlane_b32 s70, v252, 26
	v_readlane_b32 s71, v252, 27
	v_readlane_b32 s72, v252, 28
	v_readlane_b32 s73, v252, 29
	global_store_dwordx2 v[50:51], v[52:53], off
	s_and_saveexec_b64 s[28:29], s[2:3]
	s_cbranch_execz .LBB0_862
	v_lshl_add_u64 v[50:51], v[160:161], 2, s[16:17]
	s_waitcnt lgkmcnt(0)
	v_add_f32_e32 v48, v48, v49
	global_atomic_add_f32 v[50:51], v48, off
.LBB0_862:
	s_or_b64 exec, exec, s[28:29]
	v_or_b32_e32 v96, 48, v160
	v_ashrrev_i32_e32 v97, 31, v96
	v_readlane_b32 s60, v252, 16
	s_waitcnt lgkmcnt(0)
	v_lshlrev_b64 v[48:49], 13, v[96:97]
	v_readlane_b32 s74, v252, 30
	v_readlane_b32 s75, v252, 31
	v_or_b32_e32 v100, 16, v160
	v_ashrrev_i32_e32 v101, 31, v100
	v_lshl_add_u64 v[48:49], s[74:75], 0, v[48:49]
	v_lshl_add_u64 v[98:99], v[188:189], 2, v[48:49]
	global_load_dwordx4 v[60:63], v[98:99], off
	global_load_dwordx4 v[56:59], v[98:99], off offset:64
	global_load_dwordx4 v[52:55], v[98:99], off offset:512
	global_load_dwordx4 v[48:51], v[98:99], off offset:576
	s_waitcnt vmcnt(25)
	v_pk_add_f32 v[46:47], v[46:47], v[94:95]
	v_pk_add_f32 v[44:45], v[44:45], v[92:93]
	v_lshlrev_b64 v[102:103], 11, v[100:101]
	v_mul_f32_e32 v92, v45, v45
	v_mul_f32_e32 v93, v47, v47
	v_lshl_add_u64 v[102:103], v[102:103], 0, v[188:189]
	global_store_dwordx4 v[144:145], v[44:47], off nt
	v_fmac_f32_e32 v92, v44, v44
	v_fmac_f32_e32 v93, v46, v46
	v_pk_mul_f32 v[46:47], v[130:131], v[46:47]
	v_pk_mul_f32 v[44:45], v[128:129], v[44:45]
	v_add_f32_e32 v94, v92, v93
	v_cvt_pk_bf16_f32 v44, v44, v45
	v_cvt_pk_bf16_f32 v45, v46, v47
	v_lshlrev_b64 v[46:47], 1, v[102:103]
	v_lshl_add_u64 v[92:93], s[14:15], 0, v[46:47]
	v_pk_add_f32 v[42:43], v[42:43], v[90:91]
	v_pk_add_f32 v[40:41], v[40:41], v[88:89]
	global_store_dwordx2 v[92:93], v[44:45], off
	v_mul_f32_e32 v44, v41, v41
	v_mul_f32_e32 v45, v43, v43
	global_store_dwordx4 v[144:145], v[40:43], off offset:64 nt
	v_fmac_f32_e32 v44, v40, v40
	v_fmac_f32_e32 v45, v42, v42
	v_pk_mul_f32 v[42:43], v[122:123], v[42:43]
	v_pk_mul_f32 v[40:41], v[120:121], v[40:41]
	v_pk_add_f32 v[38:39], v[38:39], v[86:87]
	v_cvt_pk_bf16_f32 v40, v40, v41
	v_cvt_pk_bf16_f32 v41, v42, v43
	v_or_b32_e32 v42, 32, v46
	v_mov_b32_e32 v43, v47
	v_lshl_add_u64 v[42:43], s[14:15], 0, v[42:43]
	v_pk_add_f32 v[36:37], v[36:37], v[84:85]
	global_store_dwordx2 v[42:43], v[40:41], off
	v_mul_f32_e32 v40, v37, v37
	v_mul_f32_e32 v41, v39, v39
	global_store_dwordx4 v[144:145], v[36:39], off offset:512 nt
	v_fmac_f32_e32 v40, v36, v36
	v_fmac_f32_e32 v41, v38, v38
	v_pk_mul_f32 v[38:39], v[118:119], v[38:39]
	v_pk_mul_f32 v[36:37], v[116:117], v[36:37]
	s_waitcnt vmcnt(29)
	v_pk_add_f32 v[34:35], v[34:35], v[82:83]
	v_cvt_pk_bf16_f32 v36, v36, v37
	v_cvt_pk_bf16_f32 v37, v38, v39
	v_or_b32_e32 v38, 0x100, v46
	v_mov_b32_e32 v39, v47
	v_lshl_add_u64 v[38:39], s[14:15], 0, v[38:39]
	v_pk_add_f32 v[32:33], v[32:33], v[80:81]
	v_add_f32_e32 v44, v44, v45
	global_store_dwordx2 v[38:39], v[36:37], off
	v_mul_f32_e32 v36, v33, v33
	v_mul_f32_e32 v37, v35, v35
	v_add_f32_e32 v44, v94, v44
	v_add_f32_e32 v40, v40, v41
	v_fmac_f32_e32 v36, v32, v32
	v_fmac_f32_e32 v37, v34, v34
	v_add_f32_e32 v40, v44, v40
	v_add_f32_e32 v36, v36, v37
	v_add_f32_e32 v37, v40, v36
	ds_bpermute_b32 v38, v214, v37
	global_store_dwordx4 v[144:145], v[32:35], off offset:576 nt
	v_or_b32_e32 v46, 0x120, v46
	v_readlane_b32 s61, v252, 17
	v_pk_mul_f32 v[32:33], v[112:113], v[32:33]
	v_pk_mul_f32 v[34:35], v[114:115], v[34:35]
	v_cvt_pk_bf16_f32 v36, v32, v33
	s_waitcnt lgkmcnt(0)
	v_add_f32_e32 v32, v37, v38
	ds_bpermute_b32 v33, v213, v32
	v_cvt_pk_bf16_f32 v37, v34, v35
	v_lshl_add_u64 v[34:35], s[14:15], 0, v[46:47]
	v_readlane_b32 s62, v252, 18
	v_readlane_b32 s63, v252, 19
	v_readlane_b32 s64, v252, 20
	v_readlane_b32 s65, v252, 21
	v_readlane_b32 s66, v252, 22
	v_readlane_b32 s67, v252, 23
	v_readlane_b32 s68, v252, 24
	v_readlane_b32 s69, v252, 25
	v_readlane_b32 s70, v252, 26
	v_readlane_b32 s71, v252, 27
	v_readlane_b32 s72, v252, 28
	v_readlane_b32 s73, v252, 29
	global_store_dwordx2 v[34:35], v[36:37], off
	s_and_saveexec_b64 s[28:29], s[2:3]
	s_cbranch_execz .LBB0_864
	v_lshl_add_u64 v[34:35], v[100:101], 2, s[16:17]
	s_waitcnt lgkmcnt(0)
	v_add_f32_e32 v32, v32, v33
	global_atomic_add_f32 v[34:35], v32, off
.LBB0_864:
	s_or_b64 exec, exec, s[28:29]
	s_waitcnt vmcnt(23)
	v_pk_add_f32 v[30:31], v[30:31], v[78:79]
	v_pk_add_f32 v[28:29], v[28:29], v[76:77]
	s_waitcnt lgkmcnt(0)
	v_lshlrev_b64 v[32:33], 11, v[124:125]
	v_mul_f32_e32 v34, v29, v29
	v_mul_f32_e32 v35, v31, v31
	v_lshl_add_u64 v[32:33], v[32:33], 0, v[188:189]
	global_store_dwordx4 v[126:127], v[28:31], off nt
	v_fmac_f32_e32 v34, v28, v28
	v_fmac_f32_e32 v35, v30, v30
	v_pk_mul_f32 v[30:31], v[130:131], v[30:31]
	v_pk_mul_f32 v[28:29], v[128:129], v[28:29]
	s_waitcnt vmcnt(23)
	v_pk_add_f32 v[26:27], v[26:27], v[74:75]
	v_cvt_pk_bf16_f32 v28, v28, v29
	v_cvt_pk_bf16_f32 v29, v30, v31
	v_lshlrev_b64 v[30:31], 1, v[32:33]
	v_lshl_add_u64 v[32:33], s[14:15], 0, v[30:31]
	v_pk_add_f32 v[24:25], v[24:25], v[72:73]
	global_store_dwordx2 v[32:33], v[28:29], off
	v_mul_f32_e32 v28, v25, v25
	v_mul_f32_e32 v29, v27, v27
	global_store_dwordx4 v[126:127], v[24:27], off offset:64 nt
	v_fmac_f32_e32 v28, v24, v24
	v_fmac_f32_e32 v29, v26, v26
	v_pk_mul_f32 v[26:27], v[122:123], v[26:27]
	v_pk_mul_f32 v[24:25], v[120:121], v[24:25]
	s_waitcnt vmcnt(24)
	v_pk_add_f32 v[22:23], v[22:23], v[70:71]
	v_cvt_pk_bf16_f32 v24, v24, v25
	v_cvt_pk_bf16_f32 v25, v26, v27
	v_or_b32_e32 v26, 32, v30
	v_mov_b32_e32 v27, v31
	v_lshl_add_u64 v[26:27], s[14:15], 0, v[26:27]
	v_pk_add_f32 v[20:21], v[20:21], v[68:69]
	global_store_dwordx2 v[26:27], v[24:25], off
	v_mul_f32_e32 v24, v21, v21
	v_mul_f32_e32 v25, v23, v23
	global_store_dwordx4 v[126:127], v[20:23], off offset:512 nt
	v_fmac_f32_e32 v24, v20, v20
	v_fmac_f32_e32 v25, v22, v22
	v_pk_mul_f32 v[22:23], v[118:119], v[22:23]
	v_pk_mul_f32 v[20:21], v[116:117], v[20:21]
	s_waitcnt vmcnt(25)
	v_pk_add_f32 v[18:19], v[18:19], v[66:67]
	v_cvt_pk_bf16_f32 v20, v20, v21
	v_cvt_pk_bf16_f32 v21, v22, v23
	v_or_b32_e32 v22, 0x100, v30
	v_mov_b32_e32 v23, v31
	v_lshl_add_u64 v[22:23], s[14:15], 0, v[22:23]
	v_pk_add_f32 v[16:17], v[16:17], v[64:65]
	v_add_f32_e32 v34, v34, v35
	v_add_f32_e32 v28, v28, v29
	global_store_dwordx2 v[22:23], v[20:21], off
	v_mul_f32_e32 v20, v17, v17
	v_mul_f32_e32 v21, v19, v19
	v_add_f32_e32 v28, v34, v28
	v_add_f32_e32 v24, v24, v25
	v_fmac_f32_e32 v20, v16, v16
	v_fmac_f32_e32 v21, v18, v18
	v_add_f32_e32 v24, v28, v24
	v_add_f32_e32 v20, v20, v21
	v_add_f32_e32 v21, v24, v20
	ds_bpermute_b32 v22, v214, v21
	global_store_dwordx4 v[126:127], v[16:19], off offset:576 nt
	v_or_b32_e32 v30, 0x120, v30
	s_nop 0
	v_pk_mul_f32 v[16:17], v[112:113], v[16:17]
	v_pk_mul_f32 v[18:19], v[114:115], v[18:19]
	v_cvt_pk_bf16_f32 v20, v16, v17
	s_waitcnt lgkmcnt(0)
	v_add_f32_e32 v16, v21, v22
	ds_bpermute_b32 v17, v213, v16
	v_cvt_pk_bf16_f32 v21, v18, v19
	v_lshl_add_u64 v[18:19], s[14:15], 0, v[30:31]
	global_store_dwordx2 v[18:19], v[20:21], off
	s_and_saveexec_b64 s[28:29], s[2:3]
	s_cbranch_execz .LBB0_866
	v_lshl_add_u64 v[18:19], v[124:125], 2, s[16:17]
	s_waitcnt lgkmcnt(0)
	v_add_f32_e32 v16, v16, v17
	global_atomic_add_f32 v[18:19], v16, off
.LBB0_866:
	s_or_b64 exec, exec, s[28:29]
	s_waitcnt vmcnt(19)
	v_pk_add_f32 v[14:15], v[14:15], v[62:63]
	v_pk_add_f32 v[12:13], v[12:13], v[60:61]
	s_waitcnt lgkmcnt(0)
	v_lshlrev_b64 v[16:17], 11, v[96:97]
	v_mul_f32_e32 v18, v13, v13
	v_mul_f32_e32 v19, v15, v15
	v_lshl_add_u64 v[16:17], v[16:17], 0, v[188:189]
	global_store_dwordx4 v[98:99], v[12:15], off nt
	v_fmac_f32_e32 v18, v12, v12
	v_fmac_f32_e32 v19, v14, v14
	v_pk_mul_f32 v[14:15], v[130:131], v[14:15]
	v_pk_mul_f32 v[12:13], v[128:129], v[12:13]
	s_waitcnt vmcnt(19)
	v_pk_add_f32 v[10:11], v[10:11], v[58:59]
	v_cvt_pk_bf16_f32 v12, v12, v13
	v_cvt_pk_bf16_f32 v13, v14, v15
	v_lshlrev_b64 v[14:15], 1, v[16:17]
	v_lshl_add_u64 v[16:17], s[14:15], 0, v[14:15]
	v_pk_add_f32 v[8:9], v[8:9], v[56:57]
	global_store_dwordx2 v[16:17], v[12:13], off
	v_mul_f32_e32 v12, v9, v9
	v_mul_f32_e32 v13, v11, v11
	global_store_dwordx4 v[98:99], v[8:11], off offset:64 nt
	v_fmac_f32_e32 v12, v8, v8
	v_fmac_f32_e32 v13, v10, v10
	v_pk_mul_f32 v[10:11], v[122:123], v[10:11]
	v_pk_mul_f32 v[8:9], v[120:121], v[8:9]
	s_waitcnt vmcnt(20)
	v_pk_add_f32 v[6:7], v[6:7], v[54:55]
	v_cvt_pk_bf16_f32 v8, v8, v9
	v_cvt_pk_bf16_f32 v9, v10, v11
	v_or_b32_e32 v10, 32, v14
	v_mov_b32_e32 v11, v15
	v_lshl_add_u64 v[10:11], s[14:15], 0, v[10:11]
	v_pk_add_f32 v[4:5], v[4:5], v[52:53]
	global_store_dwordx2 v[10:11], v[8:9], off
	v_mul_f32_e32 v8, v5, v5
	v_mul_f32_e32 v9, v7, v7
	global_store_dwordx4 v[98:99], v[4:7], off offset:512 nt
	v_fmac_f32_e32 v8, v4, v4
	v_fmac_f32_e32 v9, v6, v6
	v_pk_mul_f32 v[6:7], v[118:119], v[6:7]
	v_pk_mul_f32 v[4:5], v[116:117], v[4:5]
	s_waitcnt vmcnt(21)
	v_pk_add_f32 v[2:3], v[2:3], v[50:51]
	v_cvt_pk_bf16_f32 v4, v4, v5
	v_cvt_pk_bf16_f32 v5, v6, v7
	v_or_b32_e32 v6, 0x100, v14
	v_mov_b32_e32 v7, v15
	v_lshl_add_u64 v[6:7], s[14:15], 0, v[6:7]
	v_pk_add_f32 v[0:1], v[0:1], v[48:49]
	v_add_f32_e32 v18, v18, v19
	v_add_f32_e32 v12, v12, v13
	global_store_dwordx2 v[6:7], v[4:5], off
	v_mul_f32_e32 v4, v1, v1
	v_mul_f32_e32 v5, v3, v3
	v_add_f32_e32 v12, v18, v12
	v_add_f32_e32 v8, v8, v9
	v_fmac_f32_e32 v4, v0, v0
	v_fmac_f32_e32 v5, v2, v2
	v_add_f32_e32 v8, v12, v8
	v_add_f32_e32 v4, v4, v5
	v_add_f32_e32 v5, v8, v4
	ds_bpermute_b32 v6, v214, v5
	global_store_dwordx4 v[98:99], v[0:3], off offset:576 nt
	v_or_b32_e32 v14, 0x120, v14
	s_nop 0
	v_pk_mul_f32 v[0:1], v[112:113], v[0:1]
	v_pk_mul_f32 v[2:3], v[114:115], v[2:3]
	v_cvt_pk_bf16_f32 v4, v0, v1
	s_waitcnt lgkmcnt(0)
	v_add_f32_e32 v0, v5, v6
	ds_bpermute_b32 v1, v213, v0
	v_cvt_pk_bf16_f32 v5, v2, v3
	v_lshl_add_u64 v[2:3], s[14:15], 0, v[14:15]
	global_store_dwordx2 v[2:3], v[4:5], off
	s_and_saveexec_b64 s[28:29], s[2:3]
	s_cbranch_execz .LBB0_868
	v_lshl_add_u64 v[2:3], v[96:97], 2, s[16:17]
	s_waitcnt lgkmcnt(0)
	v_add_f32_e32 v0, v0, v1
	global_atomic_add_f32 v[2:3], v0, off
